# FoX: skip-start (tiles before the first one not provably negligible by Cauchy-Schwarz |q|*max|k| + decay are not visited) + exact block skipping + hand-scheduled loop; HGRN scan spread over all 256 wo
# speedup vs baseline: 1.1565x; 1.0459x over previous
.LBB0_574:
	v_readfirstlane_b32 s2, v165
	s_nop 3
	s_lshr_b32 s2, s2, 6
	s_lshl_b32 s2, s2, 5
	s_lshl_b32 s3, s48, 8
	s_add_i32 s2, s2, s3
	s_add_i32 s20, s2, -32
	s_lshl_b32 s42, s20, 2
	s_mul_i32 s20, s20, 0x1e00
	s_add_u32 s20, s20, 0x7001200
	s_add_u32 s2, s28, s20
	s_addc_u32 s3, s29, 0
	v_and_b32_e32 v60, 31, v165
	v_mul_u32_u24_e32 v60, 0x1e00, v60
	v_bfe_u32 v61, v165, 5, 1
	v_lshl_add_u32 v60, v61, 4, v60
	v_add_u32_e32 v61, s42, v179
	global_load_dwordx4 v[64:67], v60, s[2:3] offset:0
	global_load_dwordx4 v[68:71], v60, s[2:3] offset:32
	global_load_dwordx4 v[72:75], v60, s[2:3] offset:64
	global_load_dwordx4 v[76:79], v60, s[2:3] offset:96
	ds_read_b128 v[32:35], v61
	ds_read_b128 v[36:39], v61 offset:32
	ds_read_b128 v[40:43], v61 offset:64
	ds_read_b128 v[44:47], v61 offset:96
	s_waitcnt lgkmcnt(0)
	s_waitcnt vmcnt(3)
	v_mfma_f32_32x32x16_bf16 v[32:47], v[64:67], v[96:99], v[32:47]
	s_waitcnt vmcnt(2)
	v_mfma_f32_32x32x16_bf16 v[32:47], v[68:71], v[100:103], v[32:47]
	s_waitcnt vmcnt(1)
	v_mfma_f32_32x32x16_bf16 v[32:47], v[72:75], v[104:107], v[32:47]
	s_waitcnt vmcnt(0)
	v_mfma_f32_32x32x16_bf16 v[32:47], v[76:79], v[108:111], v[32:47]
	s_nop 11
	v_max3_f32 v222, v32, v33, v34
	v_max3_f32 v222, v222, v35, v36
	v_max3_f32 v222, v222, v37, v38
	v_max3_f32 v222, v222, v39, v40
	v_max3_f32 v222, v222, v41, v42
	v_max3_f32 v222, v222, v43, v44
	v_max3_f32 v222, v222, v45, v46
	v_max_f32_e32 v222, v222, v47
	ds_bpermute_b32 v183, v180, v222
	s_waitcnt lgkmcnt(0)
	v_max_f32_e32 v183, v183, v183
	v_max_f32_e32 v182, v222, v183
	v_sub_f32_e32 v182, v182, v161
	v_add_f32_e32 v255, 0xc2800000, v182
	s_cmp_lt_u32 s48, 8
	s_cbranch_scc1 .Lfox_kpass_done
	s_mov_b64 s[2:3], 0x7001200
	v_lshl_add_u64 v[202:203], v[158:159], 0, s[2:3]
	s_mov_b64 s[2:3], 0x78000
	v_lshl_add_u64 v[204:205], v[202:203], 0, s[2:3]
	v_mov_b32_e32 v210, 0
	s_lshl_b32 s20, s48, 1
	s_add_i32 s100, s20, 1
	s_add_i32 s20, s48, 1
	s_lshr_b32 s20, s20, 1
	s_mov_b32 s101, 0
	s_mov_b32 s3, 0
	s_min_u32 s2, s101, s100
	s_mul_i32 s2, s2, 0xf0000
	s_add_i32 s101, s101, 1
	v_lshl_add_u64 v[206:207], v[202:203], 0, s[2:3]
	v_lshl_add_u64 v[208:209], v[204:205], 0, s[2:3]
	global_load_dwordx4 v[32:35], v[206:207], off
	global_load_dwordx4 v[36:39], v[208:209], off
	s_min_u32 s2, s101, s100
	s_mul_i32 s2, s2, 0xf0000
	s_add_i32 s101, s101, 1
	v_lshl_add_u64 v[206:207], v[202:203], 0, s[2:3]
	v_lshl_add_u64 v[208:209], v[204:205], 0, s[2:3]
	global_load_dwordx4 v[40:43], v[206:207], off
	global_load_dwordx4 v[44:47], v[208:209], off
	s_min_u32 s2, s101, s100
	s_mul_i32 s2, s2, 0xf0000
	s_add_i32 s101, s101, 1
	v_lshl_add_u64 v[206:207], v[202:203], 0, s[2:3]
	v_lshl_add_u64 v[208:209], v[204:205], 0, s[2:3]
	global_load_dwordx4 v[48:51], v[206:207], off
	global_load_dwordx4 v[52:55], v[208:209], off
	s_min_u32 s2, s101, s100
	s_mul_i32 s2, s2, 0xf0000
	s_add_i32 s101, s101, 1
	v_lshl_add_u64 v[206:207], v[202:203], 0, s[2:3]
	v_lshl_add_u64 v[208:209], v[204:205], 0, s[2:3]
	global_load_dwordx4 v[56:59], v[206:207], off
	global_load_dwordx4 v[60:63], v[208:209], off
	s_min_u32 s2, s101, s100
	s_mul_i32 s2, s2, 0xf0000
	s_add_i32 s101, s101, 1
	v_lshl_add_u64 v[206:207], v[202:203], 0, s[2:3]
	v_lshl_add_u64 v[208:209], v[204:205], 0, s[2:3]
	global_load_dwordx4 v[64:67], v[206:207], off
	global_load_dwordx4 v[68:71], v[208:209], off
	s_min_u32 s2, s101, s100
	s_mul_i32 s2, s2, 0xf0000
	s_add_i32 s101, s101, 1
	v_lshl_add_u64 v[206:207], v[202:203], 0, s[2:3]
	v_lshl_add_u64 v[208:209], v[204:205], 0, s[2:3]
	global_load_dwordx4 v[72:75], v[206:207], off
	global_load_dwordx4 v[76:79], v[208:209], off
	s_min_u32 s2, s101, s100
	s_mul_i32 s2, s2, 0xf0000
	s_add_i32 s101, s101, 1
	v_lshl_add_u64 v[206:207], v[202:203], 0, s[2:3]
	v_lshl_add_u64 v[208:209], v[204:205], 0, s[2:3]
	global_load_dwordx4 v[80:83], v[206:207], off
	global_load_dwordx4 v[84:87], v[208:209], off
	s_min_u32 s2, s101, s100
	s_mul_i32 s2, s2, 0xf0000
	s_add_i32 s101, s101, 1
	v_lshl_add_u64 v[206:207], v[202:203], 0, s[2:3]
	v_lshl_add_u64 v[208:209], v[204:205], 0, s[2:3]
	global_load_dwordx4 v[88:91], v[206:207], off
	global_load_dwordx4 v[92:95], v[208:209], off
.Lfox_kpass_loop:
	s_waitcnt vmcnt(15)
	v_lshlrev_b32_e32 v212, 16, v32
	v_and_b32_e32 v213, 0xffff0000, v32
	v_mul_f32_e32 v211, v212, v212
	v_fmac_f32_e32 v211, v213, v213
	v_lshlrev_b32_e32 v212, 16, v33
	v_and_b32_e32 v213, 0xffff0000, v33
	v_fmac_f32_e32 v211, v212, v212
	v_fmac_f32_e32 v211, v213, v213
	v_lshlrev_b32_e32 v212, 16, v34
	v_and_b32_e32 v213, 0xffff0000, v34
	v_fmac_f32_e32 v211, v212, v212
	v_fmac_f32_e32 v211, v213, v213
	v_lshlrev_b32_e32 v212, 16, v35
	v_and_b32_e32 v213, 0xffff0000, v35
	v_fmac_f32_e32 v211, v212, v212
	v_fmac_f32_e32 v211, v213, v213
	v_max_f32_e32 v210, v210, v211
	s_waitcnt vmcnt(14)
	v_lshlrev_b32_e32 v212, 16, v36
	v_and_b32_e32 v213, 0xffff0000, v36
	v_mul_f32_e32 v211, v212, v212
	v_fmac_f32_e32 v211, v213, v213
	v_lshlrev_b32_e32 v212, 16, v37
	v_and_b32_e32 v213, 0xffff0000, v37
	v_fmac_f32_e32 v211, v212, v212
	v_fmac_f32_e32 v211, v213, v213
	v_lshlrev_b32_e32 v212, 16, v38
	v_and_b32_e32 v213, 0xffff0000, v38
	v_fmac_f32_e32 v211, v212, v212
	v_fmac_f32_e32 v211, v213, v213
	v_lshlrev_b32_e32 v212, 16, v39
	v_and_b32_e32 v213, 0xffff0000, v39
	v_fmac_f32_e32 v211, v212, v212
	v_fmac_f32_e32 v211, v213, v213
	v_max_f32_e32 v210, v210, v211
	s_waitcnt vmcnt(13)
	v_lshlrev_b32_e32 v212, 16, v40
	v_and_b32_e32 v213, 0xffff0000, v40
	v_mul_f32_e32 v211, v212, v212
	v_fmac_f32_e32 v211, v213, v213
	v_lshlrev_b32_e32 v212, 16, v41
	v_and_b32_e32 v213, 0xffff0000, v41
	v_fmac_f32_e32 v211, v212, v212
	v_fmac_f32_e32 v211, v213, v213
	v_lshlrev_b32_e32 v212, 16, v42
	v_and_b32_e32 v213, 0xffff0000, v42
	v_fmac_f32_e32 v211, v212, v212
	v_fmac_f32_e32 v211, v213, v213
	v_lshlrev_b32_e32 v212, 16, v43
	v_and_b32_e32 v213, 0xffff0000, v43
	v_fmac_f32_e32 v211, v212, v212
	v_fmac_f32_e32 v211, v213, v213
	v_max_f32_e32 v210, v210, v211
	s_waitcnt vmcnt(12)
	v_lshlrev_b32_e32 v212, 16, v44
	v_and_b32_e32 v213, 0xffff0000, v44
	v_mul_f32_e32 v211, v212, v212
	v_fmac_f32_e32 v211, v213, v213
	v_lshlrev_b32_e32 v212, 16, v45
	v_and_b32_e32 v213, 0xffff0000, v45
	v_fmac_f32_e32 v211, v212, v212
	v_fmac_f32_e32 v211, v213, v213
	v_lshlrev_b32_e32 v212, 16, v46
	v_and_b32_e32 v213, 0xffff0000, v46
	v_fmac_f32_e32 v211, v212, v212
	v_fmac_f32_e32 v211, v213, v213
	v_lshlrev_b32_e32 v212, 16, v47
	v_and_b32_e32 v213, 0xffff0000, v47
	v_fmac_f32_e32 v211, v212, v212
	v_fmac_f32_e32 v211, v213, v213
	v_max_f32_e32 v210, v210, v211
	s_waitcnt vmcnt(11)
	v_lshlrev_b32_e32 v212, 16, v48
	v_and_b32_e32 v213, 0xffff0000, v48
	v_mul_f32_e32 v211, v212, v212
	v_fmac_f32_e32 v211, v213, v213
	v_lshlrev_b32_e32 v212, 16, v49
	v_and_b32_e32 v213, 0xffff0000, v49
	v_fmac_f32_e32 v211, v212, v212
	v_fmac_f32_e32 v211, v213, v213
	v_lshlrev_b32_e32 v212, 16, v50
	v_and_b32_e32 v213, 0xffff0000, v50
	v_fmac_f32_e32 v211, v212, v212
	v_fmac_f32_e32 v211, v213, v213
	v_lshlrev_b32_e32 v212, 16, v51
	v_and_b32_e32 v213, 0xffff0000, v51
	v_fmac_f32_e32 v211, v212, v212
	v_fmac_f32_e32 v211, v213, v213
	v_max_f32_e32 v210, v210, v211
	s_waitcnt vmcnt(10)
	v_lshlrev_b32_e32 v212, 16, v52
	v_and_b32_e32 v213, 0xffff0000, v52
	v_mul_f32_e32 v211, v212, v212
	v_fmac_f32_e32 v211, v213, v213
	v_lshlrev_b32_e32 v212, 16, v53
	v_and_b32_e32 v213, 0xffff0000, v53
	v_fmac_f32_e32 v211, v212, v212
	v_fmac_f32_e32 v211, v213, v213
	v_lshlrev_b32_e32 v212, 16, v54
	v_and_b32_e32 v213, 0xffff0000, v54
	v_fmac_f32_e32 v211, v212, v212
	v_fmac_f32_e32 v211, v213, v213
	v_lshlrev_b32_e32 v212, 16, v55
	v_and_b32_e32 v213, 0xffff0000, v55
	v_fmac_f32_e32 v211, v212, v212
	v_fmac_f32_e32 v211, v213, v213
	v_max_f32_e32 v210, v210, v211
	s_waitcnt vmcnt(9)
	v_lshlrev_b32_e32 v212, 16, v56
	v_and_b32_e32 v213, 0xffff0000, v56
	v_mul_f32_e32 v211, v212, v212
	v_fmac_f32_e32 v211, v213, v213
	v_lshlrev_b32_e32 v212, 16, v57
	v_and_b32_e32 v213, 0xffff0000, v57
	v_fmac_f32_e32 v211, v212, v212
	v_fmac_f32_e32 v211, v213, v213
	v_lshlrev_b32_e32 v212, 16, v58
	v_and_b32_e32 v213, 0xffff0000, v58
	v_fmac_f32_e32 v211, v212, v212
	v_fmac_f32_e32 v211, v213, v213
	v_lshlrev_b32_e32 v212, 16, v59
	v_and_b32_e32 v213, 0xffff0000, v59
	v_fmac_f32_e32 v211, v212, v212
	v_fmac_f32_e32 v211, v213, v213
	v_max_f32_e32 v210, v210, v211
	s_waitcnt vmcnt(8)
	v_lshlrev_b32_e32 v212, 16, v60
	v_and_b32_e32 v213, 0xffff0000, v60
	v_mul_f32_e32 v211, v212, v212
	v_fmac_f32_e32 v211, v213, v213
	v_lshlrev_b32_e32 v212, 16, v61
	v_and_b32_e32 v213, 0xffff0000, v61
	v_fmac_f32_e32 v211, v212, v212
	v_fmac_f32_e32 v211, v213, v213
	v_lshlrev_b32_e32 v212, 16, v62
	v_and_b32_e32 v213, 0xffff0000, v62
	v_fmac_f32_e32 v211, v212, v212
	v_fmac_f32_e32 v211, v213, v213
	v_lshlrev_b32_e32 v212, 16, v63
	v_and_b32_e32 v213, 0xffff0000, v63
	v_fmac_f32_e32 v211, v212, v212
	v_fmac_f32_e32 v211, v213, v213
	v_max_f32_e32 v210, v210, v211
	s_min_u32 s2, s101, s100
	s_mul_i32 s2, s2, 0xf0000
	s_add_i32 s101, s101, 1
	v_lshl_add_u64 v[206:207], v[202:203], 0, s[2:3]
	v_lshl_add_u64 v[208:209], v[204:205], 0, s[2:3]
	global_load_dwordx4 v[32:35], v[206:207], off
	global_load_dwordx4 v[36:39], v[208:209], off
	s_min_u32 s2, s101, s100
	s_mul_i32 s2, s2, 0xf0000
	s_add_i32 s101, s101, 1
	v_lshl_add_u64 v[206:207], v[202:203], 0, s[2:3]
	v_lshl_add_u64 v[208:209], v[204:205], 0, s[2:3]
	global_load_dwordx4 v[40:43], v[206:207], off
	global_load_dwordx4 v[44:47], v[208:209], off
	s_min_u32 s2, s101, s100
	s_mul_i32 s2, s2, 0xf0000
	s_add_i32 s101, s101, 1
	v_lshl_add_u64 v[206:207], v[202:203], 0, s[2:3]
	v_lshl_add_u64 v[208:209], v[204:205], 0, s[2:3]
	global_load_dwordx4 v[48:51], v[206:207], off
	global_load_dwordx4 v[52:55], v[208:209], off
	s_min_u32 s2, s101, s100
	s_mul_i32 s2, s2, 0xf0000
	s_add_i32 s101, s101, 1
	v_lshl_add_u64 v[206:207], v[202:203], 0, s[2:3]
	v_lshl_add_u64 v[208:209], v[204:205], 0, s[2:3]
	global_load_dwordx4 v[56:59], v[206:207], off
	global_load_dwordx4 v[60:63], v[208:209], off
	s_waitcnt vmcnt(15)
	v_lshlrev_b32_e32 v212, 16, v64
	v_and_b32_e32 v213, 0xffff0000, v64
	v_mul_f32_e32 v211, v212, v212
	v_fmac_f32_e32 v211, v213, v213
	v_lshlrev_b32_e32 v212, 16, v65
	v_and_b32_e32 v213, 0xffff0000, v65
	v_fmac_f32_e32 v211, v212, v212
	v_fmac_f32_e32 v211, v213, v213
	v_lshlrev_b32_e32 v212, 16, v66
	v_and_b32_e32 v213, 0xffff0000, v66
	v_fmac_f32_e32 v211, v212, v212
	v_fmac_f32_e32 v211, v213, v213
	v_lshlrev_b32_e32 v212, 16, v67
	v_and_b32_e32 v213, 0xffff0000, v67
	v_fmac_f32_e32 v211, v212, v212
	v_fmac_f32_e32 v211, v213, v213
	v_max_f32_e32 v210, v210, v211
	s_waitcnt vmcnt(14)
	v_lshlrev_b32_e32 v212, 16, v68
	v_and_b32_e32 v213, 0xffff0000, v68
	v_mul_f32_e32 v211, v212, v212
	v_fmac_f32_e32 v211, v213, v213
	v_lshlrev_b32_e32 v212, 16, v69
	v_and_b32_e32 v213, 0xffff0000, v69
	v_fmac_f32_e32 v211, v212, v212
	v_fmac_f32_e32 v211, v213, v213
	v_lshlrev_b32_e32 v212, 16, v70
	v_and_b32_e32 v213, 0xffff0000, v70
	v_fmac_f32_e32 v211, v212, v212
	v_fmac_f32_e32 v211, v213, v213
	v_lshlrev_b32_e32 v212, 16, v71
	v_and_b32_e32 v213, 0xffff0000, v71
	v_fmac_f32_e32 v211, v212, v212
	v_fmac_f32_e32 v211, v213, v213
	v_max_f32_e32 v210, v210, v211
	s_waitcnt vmcnt(13)
	v_lshlrev_b32_e32 v212, 16, v72
	v_and_b32_e32 v213, 0xffff0000, v72
	v_mul_f32_e32 v211, v212, v212
	v_fmac_f32_e32 v211, v213, v213
	v_lshlrev_b32_e32 v212, 16, v73
	v_and_b32_e32 v213, 0xffff0000, v73
	v_fmac_f32_e32 v211, v212, v212
	v_fmac_f32_e32 v211, v213, v213
	v_lshlrev_b32_e32 v212, 16, v74
	v_and_b32_e32 v213, 0xffff0000, v74
	v_fmac_f32_e32 v211, v212, v212
	v_fmac_f32_e32 v211, v213, v213
	v_lshlrev_b32_e32 v212, 16, v75
	v_and_b32_e32 v213, 0xffff0000, v75
	v_fmac_f32_e32 v211, v212, v212
	v_fmac_f32_e32 v211, v213, v213
	v_max_f32_e32 v210, v210, v211
	s_waitcnt vmcnt(12)
	v_lshlrev_b32_e32 v212, 16, v76
	v_and_b32_e32 v213, 0xffff0000, v76
	v_mul_f32_e32 v211, v212, v212
	v_fmac_f32_e32 v211, v213, v213
	v_lshlrev_b32_e32 v212, 16, v77
	v_and_b32_e32 v213, 0xffff0000, v77
	v_fmac_f32_e32 v211, v212, v212
	v_fmac_f32_e32 v211, v213, v213
	v_lshlrev_b32_e32 v212, 16, v78
	v_and_b32_e32 v213, 0xffff0000, v78
	v_fmac_f32_e32 v211, v212, v212
	v_fmac_f32_e32 v211, v213, v213
	v_lshlrev_b32_e32 v212, 16, v79
	v_and_b32_e32 v213, 0xffff0000, v79
	v_fmac_f32_e32 v211, v212, v212
	v_fmac_f32_e32 v211, v213, v213
	v_max_f32_e32 v210, v210, v211
	s_waitcnt vmcnt(11)
	v_lshlrev_b32_e32 v212, 16, v80
	v_and_b32_e32 v213, 0xffff0000, v80
	v_mul_f32_e32 v211, v212, v212
	v_fmac_f32_e32 v211, v213, v213
	v_lshlrev_b32_e32 v212, 16, v81
	v_and_b32_e32 v213, 0xffff0000, v81
	v_fmac_f32_e32 v211, v212, v212
	v_fmac_f32_e32 v211, v213, v213
	v_lshlrev_b32_e32 v212, 16, v82
	v_and_b32_e32 v213, 0xffff0000, v82
	v_fmac_f32_e32 v211, v212, v212
	v_fmac_f32_e32 v211, v213, v213
	v_lshlrev_b32_e32 v212, 16, v83
	v_and_b32_e32 v213, 0xffff0000, v83
	v_fmac_f32_e32 v211, v212, v212
	v_fmac_f32_e32 v211, v213, v213
	v_max_f32_e32 v210, v210, v211
	s_waitcnt vmcnt(10)
	v_lshlrev_b32_e32 v212, 16, v84
	v_and_b32_e32 v213, 0xffff0000, v84
	v_mul_f32_e32 v211, v212, v212
	v_fmac_f32_e32 v211, v213, v213
	v_lshlrev_b32_e32 v212, 16, v85
	v_and_b32_e32 v213, 0xffff0000, v85
	v_fmac_f32_e32 v211, v212, v212
	v_fmac_f32_e32 v211, v213, v213
	v_lshlrev_b32_e32 v212, 16, v86
	v_and_b32_e32 v213, 0xffff0000, v86
	v_fmac_f32_e32 v211, v212, v212
	v_fmac_f32_e32 v211, v213, v213
	v_lshlrev_b32_e32 v212, 16, v87
	v_and_b32_e32 v213, 0xffff0000, v87
	v_fmac_f32_e32 v211, v212, v212
	v_fmac_f32_e32 v211, v213, v213
	v_max_f32_e32 v210, v210, v211
	s_waitcnt vmcnt(9)
	v_lshlrev_b32_e32 v212, 16, v88
	v_and_b32_e32 v213, 0xffff0000, v88
	v_mul_f32_e32 v211, v212, v212
	v_fmac_f32_e32 v211, v213, v213
	v_lshlrev_b32_e32 v212, 16, v89
	v_and_b32_e32 v213, 0xffff0000, v89
	v_fmac_f32_e32 v211, v212, v212
	v_fmac_f32_e32 v211, v213, v213
	v_lshlrev_b32_e32 v212, 16, v90
	v_and_b32_e32 v213, 0xffff0000, v90
	v_fmac_f32_e32 v211, v212, v212
	v_fmac_f32_e32 v211, v213, v213
	v_lshlrev_b32_e32 v212, 16, v91
	v_and_b32_e32 v213, 0xffff0000, v91
	v_fmac_f32_e32 v211, v212, v212
	v_fmac_f32_e32 v211, v213, v213
	v_max_f32_e32 v210, v210, v211
	s_waitcnt vmcnt(8)
	v_lshlrev_b32_e32 v212, 16, v92
	v_and_b32_e32 v213, 0xffff0000, v92
	v_mul_f32_e32 v211, v212, v212
	v_fmac_f32_e32 v211, v213, v213
	v_lshlrev_b32_e32 v212, 16, v93
	v_and_b32_e32 v213, 0xffff0000, v93
	v_fmac_f32_e32 v211, v212, v212
	v_fmac_f32_e32 v211, v213, v213
	v_lshlrev_b32_e32 v212, 16, v94
	v_and_b32_e32 v213, 0xffff0000, v94
	v_fmac_f32_e32 v211, v212, v212
	v_fmac_f32_e32 v211, v213, v213
	v_lshlrev_b32_e32 v212, 16, v95
	v_and_b32_e32 v213, 0xffff0000, v95
	v_fmac_f32_e32 v211, v212, v212
	v_fmac_f32_e32 v211, v213, v213
	v_max_f32_e32 v210, v210, v211
	s_min_u32 s2, s101, s100
	s_mul_i32 s2, s2, 0xf0000
	s_add_i32 s101, s101, 1
	v_lshl_add_u64 v[206:207], v[202:203], 0, s[2:3]
	v_lshl_add_u64 v[208:209], v[204:205], 0, s[2:3]
	global_load_dwordx4 v[64:67], v[206:207], off
	global_load_dwordx4 v[68:71], v[208:209], off
	s_min_u32 s2, s101, s100
	s_mul_i32 s2, s2, 0xf0000
	s_add_i32 s101, s101, 1
	v_lshl_add_u64 v[206:207], v[202:203], 0, s[2:3]
	v_lshl_add_u64 v[208:209], v[204:205], 0, s[2:3]
	global_load_dwordx4 v[72:75], v[206:207], off
	global_load_dwordx4 v[76:79], v[208:209], off
	s_min_u32 s2, s101, s100
	s_mul_i32 s2, s2, 0xf0000
	s_add_i32 s101, s101, 1
	v_lshl_add_u64 v[206:207], v[202:203], 0, s[2:3]
	v_lshl_add_u64 v[208:209], v[204:205], 0, s[2:3]
	global_load_dwordx4 v[80:83], v[206:207], off
	global_load_dwordx4 v[84:87], v[208:209], off
	s_min_u32 s2, s101, s100
	s_mul_i32 s2, s2, 0xf0000
	s_add_i32 s101, s101, 1
	v_lshl_add_u64 v[206:207], v[202:203], 0, s[2:3]
	v_lshl_add_u64 v[208:209], v[204:205], 0, s[2:3]
	global_load_dwordx4 v[88:91], v[206:207], off
	global_load_dwordx4 v[92:95], v[208:209], off
	s_add_i32 s20, s20, -2
	s_cmp_gt_i32 s20, 0
	s_cbranch_scc1 .Lfox_kpass_loop
	s_waitcnt vmcnt(0)
	v_and_b32_e32 v214, 63, v165
	v_lshlrev_b32_e32 v214, 2, v214
	v_xor_b32_e32 v215, 32, v214
	ds_bpermute_b32 v216, v215, v210
	s_waitcnt lgkmcnt(0)
	v_max_f32_e32 v210, v210, v216
	v_xor_b32_e32 v215, 64, v214
	ds_bpermute_b32 v216, v215, v210
	s_waitcnt lgkmcnt(0)
	v_max_f32_e32 v210, v210, v216
	v_xor_b32_e32 v215, 128, v214
	ds_bpermute_b32 v216, v215, v210
	s_waitcnt lgkmcnt(0)
	v_max_f32_e32 v210, v210, v216
	v_readfirstlane_b32 s2, v165
	s_nop 3
	s_lshr_b32 s2, s2, 6
	s_lshl_b32 s2, s2, 5
	v_and_b32_e32 v215, 28, v214
	s_add_i32 s2, s2, 0x20800
	v_add_u32_e32 v215, s2, v215
	ds_write_b32 v215, v210
	s_waitcnt lgkmcnt(0)
	s_barrier
	v_add_u32_e32 v215, 0x20800, v214
	ds_read_b32 v210, v215
	v_xor_b32_e32 v215, 32, v214
	s_waitcnt lgkmcnt(0)
	ds_bpermute_b32 v216, v215, v210
	s_waitcnt lgkmcnt(0)
	v_max_f32_e32 v210, v210, v216
	v_xor_b32_e32 v215, 64, v214
	ds_bpermute_b32 v216, v215, v210
	s_waitcnt lgkmcnt(0)
	v_max_f32_e32 v210, v210, v216
	v_xor_b32_e32 v215, 128, v214
	ds_bpermute_b32 v216, v215, v210
	s_waitcnt lgkmcnt(0)
	v_max_f32_e32 v210, v210, v216
	v_xor_b32_e32 v215, 4, v214
	ds_bpermute_b32 v216, v215, v210
	s_waitcnt lgkmcnt(0)
	v_add_f32_e32 v210, v210, v216
	v_xor_b32_e32 v215, 8, v214
	ds_bpermute_b32 v216, v215, v210
	s_waitcnt lgkmcnt(0)
	v_add_f32_e32 v210, v210, v216
	v_xor_b32_e32 v215, 16, v214
	ds_bpermute_b32 v216, v215, v210
	s_waitcnt lgkmcnt(0)
	v_add_f32_e32 v210, v210, v216
	v_mov_b32_e32 v254, v210
.Lfox_kpass_done:
	v_lshlrev_b32_e32 v212, 16, v96
	v_and_b32_e32 v213, 0xffff0000, v96
	v_mul_f32_e32 v211, v212, v212
	v_fmac_f32_e32 v211, v213, v213
	v_lshlrev_b32_e32 v212, 16, v97
	v_and_b32_e32 v213, 0xffff0000, v97
	v_fmac_f32_e32 v211, v212, v212
	v_fmac_f32_e32 v211, v213, v213
	v_lshlrev_b32_e32 v212, 16, v98
	v_and_b32_e32 v213, 0xffff0000, v98
	v_fmac_f32_e32 v211, v212, v212
	v_fmac_f32_e32 v211, v213, v213
	v_lshlrev_b32_e32 v212, 16, v99
	v_and_b32_e32 v213, 0xffff0000, v99
	v_fmac_f32_e32 v211, v212, v212
	v_fmac_f32_e32 v211, v213, v213
	v_lshlrev_b32_e32 v212, 16, v100
	v_and_b32_e32 v213, 0xffff0000, v100
	v_fmac_f32_e32 v211, v212, v212
	v_fmac_f32_e32 v211, v213, v213
	v_lshlrev_b32_e32 v212, 16, v101
	v_and_b32_e32 v213, 0xffff0000, v101
	v_fmac_f32_e32 v211, v212, v212
	v_fmac_f32_e32 v211, v213, v213
	v_lshlrev_b32_e32 v212, 16, v102
	v_and_b32_e32 v213, 0xffff0000, v102
	v_fmac_f32_e32 v211, v212, v212
	v_fmac_f32_e32 v211, v213, v213
	v_lshlrev_b32_e32 v212, 16, v103
	v_and_b32_e32 v213, 0xffff0000, v103
	v_fmac_f32_e32 v211, v212, v212
	v_fmac_f32_e32 v211, v213, v213
	v_lshlrev_b32_e32 v212, 16, v104
	v_and_b32_e32 v213, 0xffff0000, v104
	v_fmac_f32_e32 v211, v212, v212
	v_fmac_f32_e32 v211, v213, v213
	v_lshlrev_b32_e32 v212, 16, v105
	v_and_b32_e32 v213, 0xffff0000, v105
	v_fmac_f32_e32 v211, v212, v212
	v_fmac_f32_e32 v211, v213, v213
	v_lshlrev_b32_e32 v212, 16, v106
	v_and_b32_e32 v213, 0xffff0000, v106
	v_fmac_f32_e32 v211, v212, v212
	v_fmac_f32_e32 v211, v213, v213
	v_lshlrev_b32_e32 v212, 16, v107
	v_and_b32_e32 v213, 0xffff0000, v107
	v_fmac_f32_e32 v211, v212, v212
	v_fmac_f32_e32 v211, v213, v213
	v_lshlrev_b32_e32 v212, 16, v108
	v_and_b32_e32 v213, 0xffff0000, v108
	v_fmac_f32_e32 v211, v212, v212
	v_fmac_f32_e32 v211, v213, v213
	v_lshlrev_b32_e32 v212, 16, v109
	v_and_b32_e32 v213, 0xffff0000, v109
	v_fmac_f32_e32 v211, v212, v212
	v_fmac_f32_e32 v211, v213, v213
	v_lshlrev_b32_e32 v212, 16, v110
	v_and_b32_e32 v213, 0xffff0000, v110
	v_fmac_f32_e32 v211, v212, v212
	v_fmac_f32_e32 v211, v213, v213
	v_lshlrev_b32_e32 v212, 16, v111
	v_and_b32_e32 v213, 0xffff0000, v111
	v_fmac_f32_e32 v211, v212, v212
	v_fmac_f32_e32 v211, v213, v213
	v_mov_b32_e32 v216, v211
	s_nop 1
	v_permlane32_swap_b32_e32 v211, v216
	v_add_f32_e32 v211, v211, v216
	v_mul_f32_e32 v211, v211, v254
	v_sqrt_f32_e32 v211, v211
	s_nop 0
	v_mul_f32_e32 v211, 0x3f880000, v211
	v_add_f32_e32 v211, 1.0, v211
	v_add_f32_e32 v210, v255, v161
	v_sub_f32_e32 v210, v210, v211
	s_lshl_b32 s100, s48, 1
	s_mov_b32 s101, 0
	s_mov_b32 s2, 508
.Lfox_j0_loop:
	v_mov_b32_e32 v215, s2
	ds_read_b32 v32, v215 offset:0
	ds_read_b32 v33, v215 offset:512
	ds_read_b32 v34, v215 offset:1024
	ds_read_b32 v35, v215 offset:1536
	s_waitcnt lgkmcnt(3)
	v_cmp_ge_f32_e32 vcc, v32, v210
	s_cbranch_vccnz .Lfox_j0_found0
	s_waitcnt lgkmcnt(2)
	v_cmp_ge_f32_e32 vcc, v33, v210
	s_cbranch_vccnz .Lfox_j0_found1
	s_waitcnt lgkmcnt(1)
	v_cmp_ge_f32_e32 vcc, v34, v210
	s_cbranch_vccnz .Lfox_j0_found2
	s_waitcnt lgkmcnt(0)
	v_cmp_ge_f32_e32 vcc, v35, v210
	s_cbranch_vccnz .Lfox_j0_found3
	s_add_i32 s101, s101, 4
	s_add_i32 s2, s2, 0x800
	s_cmp_lt_u32 s101, s100
	s_cbranch_scc1 .Lfox_j0_loop
	s_branch .Lfox_j0_found0
.Lfox_j0_found3:
	s_add_i32 s101, s101, 1

.Lfox_j0_found0:
	s_waitcnt lgkmcnt(0)
	s_min_u32 s101, s101, s100
	v_readfirstlane_b32 s2, v165
	s_nop 3
	s_lshr_b32 s2, s2, 6
	s_lshl_b32 s2, s2, 2
	s_add_i32 s2, s2, 0x20900
	v_mov_b32_e32 v215, s2
	v_mov_b32_e32 v216, s101
	ds_write_b32 v215, v216
	s_waitcnt lgkmcnt(0)
	s_barrier
	v_mov_b32_e32 v215, 0x20900
	ds_read_b128 v[32:35], v215
	ds_read_b128 v[36:39], v215 offset:16
	s_waitcnt lgkmcnt(1)
	v_min_u32_e32 v32, v32, v33
	v_min_u32_e32 v34, v34, v35
	s_waitcnt lgkmcnt(0)
	v_min_u32_e32 v36, v36, v37
	v_min_u32_e32 v38, v38, v39
	v_min_u32_e32 v32, v32, v34
	v_min_u32_e32 v36, v36, v38
	v_min_u32_e32 v32, v32, v36
	s_nop 0
	v_readfirstlane_b32 s42, v32
	s_nop 3
	s_add_i32 s42, s42, -1
.Lfox_top:
	s_cmp_lt_i32 s35, s42
	s_cbranch_scc1 .Lfox_a_nop
	s_cmp_eq_u32 s35, s42
	s_cbranch_scc1 .Lfox_a_so
	v_lshl_add_u64 v[112:113], v[158:159], 0, s[36:37]
	v_add_co_u32_e32 v116, vcc, 0x70f1000, v112
	s_nop 1
	v_addc_co_u32_e32 v117, vcc, 0, v113, vcc
	v_add_co_u32_e32 v182, vcc, 0x7169000, v112
	s_nop 1
	v_addc_co_u32_e32 v183, vcc, 0, v113, vcc
	global_load_dwordx4 v[112:115], v[116:117], off offset:512
	s_nop 0
	global_load_dwordx4 v[116:119], v[116:117], off offset:1536
	global_load_dwordx4 v[120:123], v[182:183], off offset:512
	global_load_dwordx4 v[124:127], v[182:183], off offset:1536
	ds_read_b128 v[32:35], v179
	ds_read_b128 v[36:39], v179 offset:32
	ds_read_b128 v[40:43], v179 offset:64
	ds_read_b128 v[44:47], v179 offset:96
	ds_read_b128 v[48:51], v175 offset:16384
	ds_read_b128 v[52:55], v176 offset:16384
	ds_read_b128 v[56:59], v177 offset:16384
	ds_read_b128 v[60:63], v178 offset:16384
	ds_read_b128 v[80:83], v179 offset:128
	ds_read_b128 v[84:87], v179 offset:160
	ds_read_b128 v[88:91], v179 offset:192
	ds_read_b128 v[92:95], v179 offset:224
	s_waitcnt lgkmcnt(7)
	v_mfma_f32_32x32x16_bf16 v[32:47], v[48:51], v[96:99], v[32:47]
	ds_read_b128 v[64:67], v175 offset:20480
	s_waitcnt lgkmcnt(7)
	v_mfma_f32_32x32x16_bf16 v[32:47], v[52:55], v[100:103], v[32:47]
	ds_read_b128 v[68:71], v176 offset:20480
	s_waitcnt lgkmcnt(7)
	v_mfma_f32_32x32x16_bf16 v[32:47], v[56:59], v[104:107], v[32:47]
	ds_read_b128 v[72:75], v177 offset:20480
	s_waitcnt lgkmcnt(7)
	v_mfma_f32_32x32x16_bf16 v[32:47], v[60:63], v[108:111], v[32:47]
	ds_read_b128 v[76:79], v178 offset:20480
	ds_read_b128 v[48:51], v179 offset:256
	ds_read_b128 v[52:55], v179 offset:288
	ds_read_b128 v[56:59], v179 offset:320
	ds_read_b128 v[60:63], v179 offset:352
	s_waitcnt lgkmcnt(7)
	v_mfma_f32_32x32x16_bf16 v[80:95], v[64:67], v[96:99], v[80:95]
	ds_read_b128 v[202:205], v175 offset:24576
	s_waitcnt lgkmcnt(7)
	v_mfma_f32_32x32x16_bf16 v[80:95], v[68:71], v[100:103], v[80:95]
	ds_read_b128 v[206:209], v176 offset:24576
	s_waitcnt lgkmcnt(7)
	v_mfma_f32_32x32x16_bf16 v[80:95], v[72:75], v[104:107], v[80:95]
	ds_read_b128 v[210:213], v177 offset:24576
	s_waitcnt lgkmcnt(7)
	v_mfma_f32_32x32x16_bf16 v[80:95], v[76:79], v[108:111], v[80:95]
	ds_read_b128 v[214:217], v178 offset:24576
	ds_read_b128 v[64:67], v179 offset:384
	ds_read_b128 v[68:71], v179 offset:416
	ds_read_b128 v[72:75], v179 offset:448
	ds_read_b128 v[76:79], v179 offset:480
	ds_read_b128 v[218:221], v175 offset:28672
	v_max3_f32 v222, v32, v33, v34
	v_max3_f32 v222, v222, v35, v36
	v_max3_f32 v222, v222, v37, v38
	s_waitcnt lgkmcnt(8)
	v_mfma_f32_32x32x16_bf16 v[48:63], v[202:205], v[96:99], v[48:63]
	ds_read_b128 v[202:205], v176 offset:28672
	v_max3_f32 v222, v222, v39, v40
	v_max3_f32 v222, v222, v41, v42
	s_waitcnt lgkmcnt(8)
	v_mfma_f32_32x32x16_bf16 v[48:63], v[206:209], v[100:103], v[48:63]
	ds_read_b128 v[206:209], v177 offset:28672
	v_max3_f32 v222, v222, v43, v44
	v_max3_f32 v222, v222, v45, v46
	s_waitcnt lgkmcnt(8)
	v_mfma_f32_32x32x16_bf16 v[48:63], v[210:213], v[104:107], v[48:63]
	ds_read_b128 v[210:213], v178 offset:28672
	v_max3_f32 v222, v222, v47, v80
	v_max3_f32 v222, v222, v81, v82
	s_waitcnt lgkmcnt(8)
	v_mfma_f32_32x32x16_bf16 v[48:63], v[214:217], v[108:111], v[48:63]
	v_max3_f32 v222, v222, v83, v84
	v_max3_f32 v222, v222, v85, v86
	v_max3_f32 v222, v222, v87, v88
	s_waitcnt lgkmcnt(3)
	v_mfma_f32_32x32x16_bf16 v[64:79], v[218:221], v[96:99], v[64:79]
	v_max3_f32 v222, v222, v89, v90
	v_max3_f32 v222, v222, v91, v92
	s_waitcnt lgkmcnt(2)
	v_mfma_f32_32x32x16_bf16 v[64:79], v[202:205], v[100:103], v[64:79]
	v_max3_f32 v222, v222, v93, v94
	s_waitcnt lgkmcnt(1)
	v_mfma_f32_32x32x16_bf16 v[64:79], v[206:209], v[104:107], v[64:79]
	s_waitcnt lgkmcnt(0)
	v_mfma_f32_32x32x16_bf16 v[64:79], v[210:213], v[108:111], v[64:79]
	v_add_u32_e32 v218, 0xc000, v181
	v_max3_f32 v222, v222, v95, v48
	v_max3_f32 v222, v222, v49, v50
	v_max3_f32 v222, v222, v51, v52
	v_max3_f32 v222, v222, v53, v54
	v_max3_f32 v222, v222, v55, v56
	v_max3_f32 v222, v222, v57, v58
	v_max3_f32 v222, v222, v59, v60
	v_max3_f32 v222, v222, v61, v62
	s_nop 2
	v_max3_f32 v222, v222, v63, v64
	v_max3_f32 v222, v222, v65, v66
	v_max3_f32 v222, v222, v67, v68
	v_max3_f32 v222, v222, v69, v70
	v_max3_f32 v222, v222, v71, v72
	v_max3_f32 v222, v222, v73, v74
	v_max3_f32 v222, v222, v75, v76
	v_max3_f32 v222, v222, v77, v78
	v_max_f32_e32 v222, v222, v79
	ds_bpermute_b32 v183, v180, v222
	s_waitcnt lgkmcnt(0)
	v_max_f32_e32 v183, v183, v183
	v_max_f32_e32 v182, v222, v183
	v_sub_f32_e32 v182, v182, v161
	v_cmp_gt_f32_e32 vcc, v182, v255
	s_cbranch_vccz .Lfox_a_skip
	ds_read_b64_tr_b16 v[202:203], v218 offset:0
	ds_read_b64_tr_b16 v[204:205], v218 offset:1536
	ds_read_b64_tr_b16 v[206:207], v218 offset:64
	ds_read_b64_tr_b16 v[208:209], v218 offset:1600
	ds_read_b64_tr_b16 v[210:211], v218 offset:3072
	ds_read_b64_tr_b16 v[212:213], v218 offset:4608
	ds_read_b64_tr_b16 v[214:215], v218 offset:3136
	ds_read_b64_tr_b16 v[216:217], v218 offset:4672
	v_add_f32_e32 v183, 0x40c00000, v164
	v_cmp_gt_f32_e32 vcc, v182, v183
	s_cbranch_vccz .Lfox_a_pv
	v_max_f32_e32 v182, v182, v182
	v_max_f32_e32 v183, v164, v164
	v_max_f32_e32 v182, v183, v182
	v_sub_f32_e32 v164, v164, v182
	v_exp_f32_e32 v164, v164
	s_nop 0
	v_mul_f32_e32 v163, v163, v164
	v_pk_mul_f32 v[30:31], v[30:31], v[164:165] op_sel_hi:[1,0]
	v_pk_mul_f32 v[28:29], v[28:29], v[164:165] op_sel_hi:[1,0]
	v_pk_mul_f32 v[26:27], v[26:27], v[164:165] op_sel_hi:[1,0]
	v_pk_mul_f32 v[24:25], v[24:25], v[164:165] op_sel_hi:[1,0]
	v_pk_mul_f32 v[22:23], v[22:23], v[164:165] op_sel_hi:[1,0]
	v_pk_mul_f32 v[20:21], v[20:21], v[164:165] op_sel_hi:[1,0]
	v_pk_mul_f32 v[18:19], v[18:19], v[164:165] op_sel_hi:[1,0]
	v_pk_mul_f32 v[16:17], v[16:17], v[164:165] op_sel_hi:[1,0]
	v_pk_mul_f32 v[14:15], v[14:15], v[164:165] op_sel_hi:[1,0]
	v_pk_mul_f32 v[12:13], v[12:13], v[164:165] op_sel_hi:[1,0]
	v_pk_mul_f32 v[10:11], v[10:11], v[164:165] op_sel_hi:[1,0]
	v_pk_mul_f32 v[8:9], v[8:9], v[164:165] op_sel_hi:[1,0]
	v_pk_mul_f32 v[6:7], v[6:7], v[164:165] op_sel_hi:[1,0]
	v_pk_mul_f32 v[4:5], v[4:5], v[164:165] op_sel_hi:[1,0]
	v_pk_mul_f32 v[2:3], v[2:3], v[164:165] op_sel_hi:[1,0]
	v_pk_mul_f32 v[0:1], v[0:1], v[164:165] op_sel_hi:[1,0]
	v_mov_b32_e32 v164, v182
.Lfox_a_pv:
	v_sub_f32_e64 v222, -v161, v164
	v_add_f32_e32 v32, v32, v222
	v_add_f32_e32 v33, v33, v222
	v_add_f32_e32 v34, v34, v222
	v_add_f32_e32 v35, v35, v222
	v_add_f32_e32 v36, v36, v222
	v_add_f32_e32 v37, v37, v222
	v_add_f32_e32 v38, v38, v222
	v_add_f32_e32 v39, v39, v222
	v_exp_f32_e32 v32, v32
	v_exp_f32_e32 v33, v33
	v_exp_f32_e32 v34, v34
	v_exp_f32_e32 v35, v35
	v_exp_f32_e32 v36, v36
	v_exp_f32_e32 v37, v37
	v_exp_f32_e32 v38, v38
	v_exp_f32_e32 v39, v39
	v_add_f32_e32 v182, v32, v33
	v_add_f32_e32 v183, v34, v35
	v_add_f32_e32 v182, v182, v36
	v_add_f32_e32 v183, v183, v37
	v_add_f32_e32 v182, v182, v38
	v_add_f32_e32 v183, v183, v39
	v_cvt_pk_bf16_f32 v32, v32, v33
	v_cvt_pk_bf16_f32 v33, v34, v35
	v_cvt_pk_bf16_f32 v34, v36, v37
	v_cvt_pk_bf16_f32 v35, v38, v39
	s_waitcnt lgkmcnt(6)
	s_nop 0
	v_mfma_f32_32x32x16_bf16 v[16:31], v[202:205], v[32:35], v[16:31]
	v_add_f32_e32 v40, v40, v222
	v_add_f32_e32 v41, v41, v222
	v_add_f32_e32 v42, v42, v222
	v_add_f32_e32 v43, v43, v222
	v_add_f32_e32 v44, v44, v222
	v_add_f32_e32 v45, v45, v222
	v_add_f32_e32 v46, v46, v222
	v_add_f32_e32 v47, v47, v222
	v_exp_f32_e32 v40, v40
	v_exp_f32_e32 v41, v41
	v_exp_f32_e32 v42, v42
	v_exp_f32_e32 v43, v43
	v_exp_f32_e32 v44, v44
	v_exp_f32_e32 v45, v45
	v_exp_f32_e32 v46, v46
	v_exp_f32_e32 v47, v47
	s_waitcnt lgkmcnt(4)
	v_mfma_f32_32x32x16_bf16 v[0:15], v[206:209], v[32:35], v[0:15]
	ds_read_b64_tr_b16 v[202:203], v218 offset:6144
	ds_read_b64_tr_b16 v[204:205], v218 offset:7680
	ds_read_b64_tr_b16 v[206:207], v218 offset:6208
	ds_read_b64_tr_b16 v[208:209], v218 offset:7744
	v_add_f32_e32 v182, v182, v40
	v_add_f32_e32 v183, v183, v41
	v_add_f32_e32 v182, v182, v42
	v_add_f32_e32 v183, v183, v43
	v_add_f32_e32 v182, v182, v44
	v_add_f32_e32 v183, v183, v45
	v_add_f32_e32 v182, v182, v46
	v_add_f32_e32 v183, v183, v47
	v_cvt_pk_bf16_f32 v40, v40, v41
	v_cvt_pk_bf16_f32 v41, v42, v43
	v_cvt_pk_bf16_f32 v42, v44, v45
	v_cvt_pk_bf16_f32 v43, v46, v47
	s_waitcnt lgkmcnt(6)
	s_nop 0
	v_mfma_f32_32x32x16_bf16 v[16:31], v[210:213], v[40:43], v[16:31]
	v_add_f32_e32 v80, v80, v222
	v_add_f32_e32 v81, v81, v222
	v_add_f32_e32 v82, v82, v222
	v_add_f32_e32 v83, v83, v222
	v_add_f32_e32 v84, v84, v222
	v_add_f32_e32 v85, v85, v222
	v_add_f32_e32 v86, v86, v222
	v_add_f32_e32 v87, v87, v222
	v_exp_f32_e32 v80, v80
	v_exp_f32_e32 v81, v81
	v_exp_f32_e32 v82, v82
	v_exp_f32_e32 v83, v83
	v_exp_f32_e32 v84, v84
	v_exp_f32_e32 v85, v85
	v_exp_f32_e32 v86, v86
	v_exp_f32_e32 v87, v87
	s_waitcnt lgkmcnt(4)
	v_mfma_f32_32x32x16_bf16 v[0:15], v[214:217], v[40:43], v[0:15]
	ds_read_b64_tr_b16 v[210:211], v218 offset:9216
	ds_read_b64_tr_b16 v[212:213], v218 offset:10752
	ds_read_b64_tr_b16 v[214:215], v218 offset:9280
	ds_read_b64_tr_b16 v[216:217], v218 offset:10816
	v_add_f32_e32 v182, v182, v80
	v_add_f32_e32 v183, v183, v81
	v_add_f32_e32 v182, v182, v82
	v_add_f32_e32 v183, v183, v83
	v_add_f32_e32 v182, v182, v84
	v_add_f32_e32 v183, v183, v85
	v_add_f32_e32 v182, v182, v86
	v_add_f32_e32 v183, v183, v87
	v_cvt_pk_bf16_f32 v80, v80, v81
	v_cvt_pk_bf16_f32 v81, v82, v83
	v_cvt_pk_bf16_f32 v82, v84, v85
	v_cvt_pk_bf16_f32 v83, v86, v87
	s_waitcnt lgkmcnt(6)
	s_nop 0
	v_mfma_f32_32x32x16_bf16 v[16:31], v[202:205], v[80:83], v[16:31]
	v_add_f32_e32 v88, v88, v222
	v_add_f32_e32 v89, v89, v222
	v_add_f32_e32 v90, v90, v222
	v_add_f32_e32 v91, v91, v222
	v_add_f32_e32 v92, v92, v222
	v_add_f32_e32 v93, v93, v222
	v_add_f32_e32 v94, v94, v222
	v_add_f32_e32 v95, v95, v222
	v_exp_f32_e32 v88, v88
	v_exp_f32_e32 v89, v89
	v_exp_f32_e32 v90, v90
	v_exp_f32_e32 v91, v91
	v_exp_f32_e32 v92, v92
	v_exp_f32_e32 v93, v93
	v_exp_f32_e32 v94, v94
	v_exp_f32_e32 v95, v95
	s_waitcnt lgkmcnt(4)
	v_mfma_f32_32x32x16_bf16 v[0:15], v[206:209], v[80:83], v[0:15]
	ds_read_b64_tr_b16 v[202:203], v218 offset:12288
	ds_read_b64_tr_b16 v[204:205], v218 offset:13824
	ds_read_b64_tr_b16 v[206:207], v218 offset:12352
	ds_read_b64_tr_b16 v[208:209], v218 offset:13888
	v_add_f32_e32 v182, v182, v88
	v_add_f32_e32 v183, v183, v89
	v_add_f32_e32 v182, v182, v90
	v_add_f32_e32 v183, v183, v91
	v_add_f32_e32 v182, v182, v92
	v_add_f32_e32 v183, v183, v93
	v_add_f32_e32 v182, v182, v94
	v_add_f32_e32 v183, v183, v95
	v_cvt_pk_bf16_f32 v88, v88, v89
	v_cvt_pk_bf16_f32 v89, v90, v91
	v_cvt_pk_bf16_f32 v90, v92, v93
	v_cvt_pk_bf16_f32 v91, v94, v95
	s_waitcnt lgkmcnt(6)
	s_nop 0
	v_mfma_f32_32x32x16_bf16 v[16:31], v[210:213], v[88:91], v[16:31]
	v_add_f32_e32 v48, v48, v222
	v_add_f32_e32 v49, v49, v222
	v_add_f32_e32 v50, v50, v222
	v_add_f32_e32 v51, v51, v222
	v_add_f32_e32 v52, v52, v222
	v_add_f32_e32 v53, v53, v222
	v_add_f32_e32 v54, v54, v222
	v_add_f32_e32 v55, v55, v222
	v_exp_f32_e32 v48, v48
	v_exp_f32_e32 v49, v49
	v_exp_f32_e32 v50, v50
	v_exp_f32_e32 v51, v51
	v_exp_f32_e32 v52, v52
	v_exp_f32_e32 v53, v53
	v_exp_f32_e32 v54, v54
	v_exp_f32_e32 v55, v55
	s_waitcnt lgkmcnt(4)
	v_mfma_f32_32x32x16_bf16 v[0:15], v[214:217], v[88:91], v[0:15]
	ds_read_b64_tr_b16 v[210:211], v218 offset:15360
	ds_read_b64_tr_b16 v[212:213], v218 offset:16896
	ds_read_b64_tr_b16 v[214:215], v218 offset:15424
	ds_read_b64_tr_b16 v[216:217], v218 offset:16960
	v_add_f32_e32 v182, v182, v48
	v_add_f32_e32 v183, v183, v49
	v_add_f32_e32 v182, v182, v50
	v_add_f32_e32 v183, v183, v51
	v_add_f32_e32 v182, v182, v52
	v_add_f32_e32 v183, v183, v53
	v_add_f32_e32 v182, v182, v54
	v_add_f32_e32 v183, v183, v55
	v_cvt_pk_bf16_f32 v48, v48, v49
	v_cvt_pk_bf16_f32 v49, v50, v51
	v_cvt_pk_bf16_f32 v50, v52, v53
	v_cvt_pk_bf16_f32 v51, v54, v55
	s_waitcnt lgkmcnt(6)
	s_nop 0
	v_mfma_f32_32x32x16_bf16 v[16:31], v[202:205], v[48:51], v[16:31]
	v_add_f32_e32 v56, v56, v222
	v_add_f32_e32 v57, v57, v222
	v_add_f32_e32 v58, v58, v222
	v_add_f32_e32 v59, v59, v222
	v_add_f32_e32 v60, v60, v222
	v_add_f32_e32 v61, v61, v222
	v_add_f32_e32 v62, v62, v222
	v_add_f32_e32 v63, v63, v222
	v_exp_f32_e32 v56, v56
	v_exp_f32_e32 v57, v57
	v_exp_f32_e32 v58, v58
	v_exp_f32_e32 v59, v59
	v_exp_f32_e32 v60, v60
	v_exp_f32_e32 v61, v61
	v_exp_f32_e32 v62, v62
	v_exp_f32_e32 v63, v63
	s_waitcnt lgkmcnt(4)
	v_mfma_f32_32x32x16_bf16 v[0:15], v[206:209], v[48:51], v[0:15]
	ds_read_b64_tr_b16 v[202:203], v218 offset:18432
	ds_read_b64_tr_b16 v[204:205], v218 offset:19968
	ds_read_b64_tr_b16 v[206:207], v218 offset:18496
	ds_read_b64_tr_b16 v[208:209], v218 offset:20032
	v_add_f32_e32 v182, v182, v56
	v_add_f32_e32 v183, v183, v57
	v_add_f32_e32 v182, v182, v58
	v_add_f32_e32 v183, v183, v59
	v_add_f32_e32 v182, v182, v60
	v_add_f32_e32 v183, v183, v61
	v_add_f32_e32 v182, v182, v62
	v_add_f32_e32 v183, v183, v63
	v_cvt_pk_bf16_f32 v56, v56, v57
	v_cvt_pk_bf16_f32 v57, v58, v59
	v_cvt_pk_bf16_f32 v58, v60, v61
	v_cvt_pk_bf16_f32 v59, v62, v63
	s_waitcnt lgkmcnt(6)
	s_nop 0
	v_mfma_f32_32x32x16_bf16 v[16:31], v[210:213], v[56:59], v[16:31]
	v_add_f32_e32 v64, v64, v222
	v_add_f32_e32 v65, v65, v222
	v_add_f32_e32 v66, v66, v222
	v_add_f32_e32 v67, v67, v222
	v_add_f32_e32 v68, v68, v222
	v_add_f32_e32 v69, v69, v222
	v_add_f32_e32 v70, v70, v222
	v_add_f32_e32 v71, v71, v222
	v_exp_f32_e32 v64, v64
	v_exp_f32_e32 v65, v65
	v_exp_f32_e32 v66, v66
	v_exp_f32_e32 v67, v67
	v_exp_f32_e32 v68, v68
	v_exp_f32_e32 v69, v69
	v_exp_f32_e32 v70, v70
	v_exp_f32_e32 v71, v71
	s_waitcnt lgkmcnt(4)
	v_mfma_f32_32x32x16_bf16 v[0:15], v[214:217], v[56:59], v[0:15]
	ds_read_b64_tr_b16 v[210:211], v218 offset:21504
	ds_read_b64_tr_b16 v[212:213], v218 offset:23040
	ds_read_b64_tr_b16 v[214:215], v218 offset:21568
	ds_read_b64_tr_b16 v[216:217], v218 offset:23104
	v_add_f32_e32 v182, v182, v64
	v_add_f32_e32 v183, v183, v65
	v_add_f32_e32 v182, v182, v66
	v_add_f32_e32 v183, v183, v67
	v_add_f32_e32 v182, v182, v68
	v_add_f32_e32 v183, v183, v69
	v_add_f32_e32 v182, v182, v70
	v_add_f32_e32 v183, v183, v71
	v_cvt_pk_bf16_f32 v64, v64, v65
	v_cvt_pk_bf16_f32 v65, v66, v67
	v_cvt_pk_bf16_f32 v66, v68, v69
	v_cvt_pk_bf16_f32 v67, v70, v71
	s_waitcnt lgkmcnt(6)
	s_nop 0
	v_mfma_f32_32x32x16_bf16 v[16:31], v[202:205], v[64:67], v[16:31]
	v_add_f32_e32 v72, v72, v222
	v_add_f32_e32 v73, v73, v222
	v_add_f32_e32 v74, v74, v222
	v_add_f32_e32 v75, v75, v222
	v_add_f32_e32 v76, v76, v222
	v_add_f32_e32 v77, v77, v222
	v_add_f32_e32 v78, v78, v222
	v_add_f32_e32 v79, v79, v222
	v_exp_f32_e32 v72, v72
	v_exp_f32_e32 v73, v73
	v_exp_f32_e32 v74, v74
	v_exp_f32_e32 v75, v75
	v_exp_f32_e32 v76, v76
	v_exp_f32_e32 v77, v77
	v_exp_f32_e32 v78, v78
	v_exp_f32_e32 v79, v79
	s_waitcnt lgkmcnt(4)
	v_mfma_f32_32x32x16_bf16 v[0:15], v[206:209], v[64:67], v[0:15]
	v_add_f32_e32 v182, v182, v72
	v_add_f32_e32 v183, v183, v73
	v_add_f32_e32 v182, v182, v74
	v_add_f32_e32 v183, v183, v75
	v_add_f32_e32 v182, v182, v76
	v_add_f32_e32 v183, v183, v77
	v_add_f32_e32 v182, v182, v78
	v_add_f32_e32 v183, v183, v79
	v_cvt_pk_bf16_f32 v72, v72, v73
	v_cvt_pk_bf16_f32 v73, v74, v75
	v_cvt_pk_bf16_f32 v74, v76, v77
	v_cvt_pk_bf16_f32 v75, v78, v79
	s_waitcnt lgkmcnt(2)
	s_nop 0
	v_mfma_f32_32x32x16_bf16 v[16:31], v[210:213], v[72:75], v[16:31]
	s_waitcnt lgkmcnt(0)
	v_mfma_f32_32x32x16_bf16 v[0:15], v[214:217], v[72:75], v[0:15]
	v_add_f32_e32 v163, v163, v182
	v_add_f32_e32 v163, v163, v183
.Lfox_a_skip:
	s_waitcnt vmcnt(3)
	ds_write_b128 v147, v[112:115] offset:32768
	s_waitcnt vmcnt(1)
	ds_write_b128 v147, v[120:123] offset:40960
	v_add_u32_e32 v222, 0x12000, v153
	ds_write_b128 v222, v[116:119]
	s_waitcnt vmcnt(0)
	ds_write_b128 v222, v[124:127] offset:12288
	s_add_u32 s36, s36, 0xf0000
	s_addc_u32 s37, s37, 0
	s_add_i32 s35, s35, 1
	s_waitcnt lgkmcnt(0)
	s_barrier
.Lfox_a_end:
	s_cmp_lt_i32 s35, s42
	s_cbranch_scc1 .Lfox_b_nop
	s_cmp_eq_u32 s35, s42
	s_cbranch_scc1 .Lfox_b_so
	v_lshl_add_u64 v[112:113], v[158:159], 0, s[36:37]
	v_add_co_u32_e32 v116, vcc, 0x70f1000, v112
	s_nop 1
	v_addc_co_u32_e32 v117, vcc, 0, v113, vcc
	v_add_co_u32_e32 v182, vcc, 0x7169000, v112
	s_nop 1
	v_addc_co_u32_e32 v183, vcc, 0, v113, vcc
	global_load_dwordx4 v[112:115], v[116:117], off offset:512
	s_nop 0
	global_load_dwordx4 v[116:119], v[116:117], off offset:1536
	global_load_dwordx4 v[120:123], v[182:183], off offset:512
	global_load_dwordx4 v[124:127], v[182:183], off offset:1536
	ds_read_b128 v[32:35], v179 offset:512
	ds_read_b128 v[36:39], v179 offset:544
	ds_read_b128 v[40:43], v179 offset:576
	ds_read_b128 v[44:47], v179 offset:608
	ds_read_b128 v[48:51], v175 offset:32768
	ds_read_b128 v[52:55], v176 offset:32768
	ds_read_b128 v[56:59], v177 offset:32768
	ds_read_b128 v[60:63], v178 offset:32768
	ds_read_b128 v[80:83], v179 offset:640
	ds_read_b128 v[84:87], v179 offset:672
	ds_read_b128 v[88:91], v179 offset:704
	ds_read_b128 v[92:95], v179 offset:736
	s_waitcnt lgkmcnt(7)
	v_mfma_f32_32x32x16_bf16 v[32:47], v[48:51], v[96:99], v[32:47]
	ds_read_b128 v[64:67], v175 offset:36864
	s_waitcnt lgkmcnt(7)
	v_mfma_f32_32x32x16_bf16 v[32:47], v[52:55], v[100:103], v[32:47]
	ds_read_b128 v[68:71], v176 offset:36864
	s_waitcnt lgkmcnt(7)
	v_mfma_f32_32x32x16_bf16 v[32:47], v[56:59], v[104:107], v[32:47]
	ds_read_b128 v[72:75], v177 offset:36864
	s_waitcnt lgkmcnt(7)
	v_mfma_f32_32x32x16_bf16 v[32:47], v[60:63], v[108:111], v[32:47]
	ds_read_b128 v[76:79], v178 offset:36864
	ds_read_b128 v[48:51], v179 offset:768
	ds_read_b128 v[52:55], v179 offset:800
	ds_read_b128 v[56:59], v179 offset:832
	ds_read_b128 v[60:63], v179 offset:864
	s_waitcnt lgkmcnt(7)
	v_mfma_f32_32x32x16_bf16 v[80:95], v[64:67], v[96:99], v[80:95]
	ds_read_b128 v[202:205], v175 offset:40960
	s_waitcnt lgkmcnt(7)
	v_mfma_f32_32x32x16_bf16 v[80:95], v[68:71], v[100:103], v[80:95]
	ds_read_b128 v[206:209], v176 offset:40960
	s_waitcnt lgkmcnt(7)
	v_mfma_f32_32x32x16_bf16 v[80:95], v[72:75], v[104:107], v[80:95]
	ds_read_b128 v[210:213], v177 offset:40960
	s_waitcnt lgkmcnt(7)
	v_mfma_f32_32x32x16_bf16 v[80:95], v[76:79], v[108:111], v[80:95]
	ds_read_b128 v[214:217], v178 offset:40960
	ds_read_b128 v[64:67], v179 offset:896
	ds_read_b128 v[68:71], v179 offset:928
	ds_read_b128 v[72:75], v179 offset:960
	ds_read_b128 v[76:79], v179 offset:992
	ds_read_b128 v[218:221], v175 offset:45056
	v_max3_f32 v222, v32, v33, v34
	v_max3_f32 v222, v222, v35, v36
	v_max3_f32 v222, v222, v37, v38
	s_waitcnt lgkmcnt(8)
	v_mfma_f32_32x32x16_bf16 v[48:63], v[202:205], v[96:99], v[48:63]
	ds_read_b128 v[202:205], v176 offset:45056
	v_max3_f32 v222, v222, v39, v40
	v_max3_f32 v222, v222, v41, v42
	s_waitcnt lgkmcnt(8)
	v_mfma_f32_32x32x16_bf16 v[48:63], v[206:209], v[100:103], v[48:63]
	ds_read_b128 v[206:209], v177 offset:45056
	v_max3_f32 v222, v222, v43, v44
	v_max3_f32 v222, v222, v45, v46
	s_waitcnt lgkmcnt(8)
	v_mfma_f32_32x32x16_bf16 v[48:63], v[210:213], v[104:107], v[48:63]
	ds_read_b128 v[210:213], v178 offset:45056
	v_max3_f32 v222, v222, v47, v80
	v_max3_f32 v222, v222, v81, v82
	s_waitcnt lgkmcnt(8)
	v_mfma_f32_32x32x16_bf16 v[48:63], v[214:217], v[108:111], v[48:63]
	v_max3_f32 v222, v222, v83, v84
	v_max3_f32 v222, v222, v85, v86
	v_max3_f32 v222, v222, v87, v88
	s_waitcnt lgkmcnt(3)
	v_mfma_f32_32x32x16_bf16 v[64:79], v[218:221], v[96:99], v[64:79]
	v_max3_f32 v222, v222, v89, v90
	v_max3_f32 v222, v222, v91, v92
	s_waitcnt lgkmcnt(2)
	v_mfma_f32_32x32x16_bf16 v[64:79], v[202:205], v[100:103], v[64:79]
	v_max3_f32 v222, v222, v93, v94
	s_waitcnt lgkmcnt(1)
	v_mfma_f32_32x32x16_bf16 v[64:79], v[206:209], v[104:107], v[64:79]
	s_waitcnt lgkmcnt(0)
	v_mfma_f32_32x32x16_bf16 v[64:79], v[210:213], v[108:111], v[64:79]
	v_add_u32_e32 v218, 0x12000, v181
	v_max3_f32 v222, v222, v95, v48
	v_max3_f32 v222, v222, v49, v50
	v_max3_f32 v222, v222, v51, v52
	v_max3_f32 v222, v222, v53, v54
	v_max3_f32 v222, v222, v55, v56
	v_max3_f32 v222, v222, v57, v58
	v_max3_f32 v222, v222, v59, v60
	v_max3_f32 v222, v222, v61, v62
	s_nop 2
	v_max3_f32 v222, v222, v63, v64
	v_max3_f32 v222, v222, v65, v66
	v_max3_f32 v222, v222, v67, v68
	v_max3_f32 v222, v222, v69, v70
	v_max3_f32 v222, v222, v71, v72
	v_max3_f32 v222, v222, v73, v74
	v_max3_f32 v222, v222, v75, v76
	v_max3_f32 v222, v222, v77, v78
	v_max_f32_e32 v222, v222, v79
	ds_bpermute_b32 v183, v180, v222
	s_waitcnt lgkmcnt(0)
	v_max_f32_e32 v183, v183, v183
	v_max_f32_e32 v182, v222, v183
	v_sub_f32_e32 v182, v182, v161
	v_cmp_gt_f32_e32 vcc, v182, v255
	s_cbranch_vccz .Lfox_b_skip
	ds_read_b64_tr_b16 v[202:203], v218 offset:0
	ds_read_b64_tr_b16 v[204:205], v218 offset:1536
	ds_read_b64_tr_b16 v[206:207], v218 offset:64
	ds_read_b64_tr_b16 v[208:209], v218 offset:1600
	ds_read_b64_tr_b16 v[210:211], v218 offset:3072
	ds_read_b64_tr_b16 v[212:213], v218 offset:4608
	ds_read_b64_tr_b16 v[214:215], v218 offset:3136
	ds_read_b64_tr_b16 v[216:217], v218 offset:4672
	v_add_f32_e32 v183, 0x40c00000, v164
	v_cmp_gt_f32_e32 vcc, v182, v183
	s_cbranch_vccz .Lfox_b_pv
	v_max_f32_e32 v182, v182, v182
	v_max_f32_e32 v183, v164, v164
	v_max_f32_e32 v182, v183, v182
	v_sub_f32_e32 v164, v164, v182
	v_exp_f32_e32 v164, v164
	s_nop 0
	v_mul_f32_e32 v163, v163, v164
	v_pk_mul_f32 v[30:31], v[30:31], v[164:165] op_sel_hi:[1,0]
	v_pk_mul_f32 v[28:29], v[28:29], v[164:165] op_sel_hi:[1,0]
	v_pk_mul_f32 v[26:27], v[26:27], v[164:165] op_sel_hi:[1,0]
	v_pk_mul_f32 v[24:25], v[24:25], v[164:165] op_sel_hi:[1,0]
	v_pk_mul_f32 v[22:23], v[22:23], v[164:165] op_sel_hi:[1,0]
	v_pk_mul_f32 v[20:21], v[20:21], v[164:165] op_sel_hi:[1,0]
	v_pk_mul_f32 v[18:19], v[18:19], v[164:165] op_sel_hi:[1,0]
	v_pk_mul_f32 v[16:17], v[16:17], v[164:165] op_sel_hi:[1,0]
	v_pk_mul_f32 v[14:15], v[14:15], v[164:165] op_sel_hi:[1,0]
	v_pk_mul_f32 v[12:13], v[12:13], v[164:165] op_sel_hi:[1,0]
	v_pk_mul_f32 v[10:11], v[10:11], v[164:165] op_sel_hi:[1,0]
	v_pk_mul_f32 v[8:9], v[8:9], v[164:165] op_sel_hi:[1,0]
	v_pk_mul_f32 v[6:7], v[6:7], v[164:165] op_sel_hi:[1,0]
	v_pk_mul_f32 v[4:5], v[4:5], v[164:165] op_sel_hi:[1,0]
	v_pk_mul_f32 v[2:3], v[2:3], v[164:165] op_sel_hi:[1,0]
	v_pk_mul_f32 v[0:1], v[0:1], v[164:165] op_sel_hi:[1,0]
	v_mov_b32_e32 v164, v182

.Lfox_b_skip:
	s_waitcnt vmcnt(3)
	ds_write_b128 v147, v[112:115] offset:16384
	s_waitcnt vmcnt(1)
	ds_write_b128 v147, v[120:123] offset:24576
	v_add_u32_e32 v222, 0xc000, v153
	ds_write_b128 v222, v[116:119]
	s_waitcnt vmcnt(0)
	ds_write_b128 v222, v[124:127] offset:12288
	s_add_u32 s36, s36, 0xf0000
	s_addc_u32 s37, s37, 0
	s_add_i32 s35, s35, 1
	v_add_u32_e32 v179, 0x400, v179
	s_waitcnt lgkmcnt(0)
	s_barrier
.Lfox_b_end:
	s_cmp_eq_u32 s80, s36
	s_cbranch_scc0 .Lfox_top
	s_branch .LBB0_576
.Lfox_a_nop:
	s_add_u32 s36, s36, 0xf0000
	s_addc_u32 s37, s37, 0
	s_add_i32 s35, s35, 1
	s_branch .Lfox_a_end
.Lfox_a_so:
	v_lshl_add_u64 v[112:113], v[158:159], 0, s[36:37]
	v_add_co_u32_e32 v116, vcc, 0x70f1000, v112
	s_nop 1
	v_addc_co_u32_e32 v117, vcc, 0, v113, vcc
	v_add_co_u32_e32 v182, vcc, 0x7169000, v112
	s_nop 1
	v_addc_co_u32_e32 v183, vcc, 0, v113, vcc
	global_load_dwordx4 v[112:115], v[116:117], off offset:512
	s_nop 0
	global_load_dwordx4 v[116:119], v[116:117], off offset:1536
	global_load_dwordx4 v[120:123], v[182:183], off offset:512
	global_load_dwordx4 v[124:127], v[182:183], off offset:1536
	s_waitcnt vmcnt(3)
	ds_write_b128 v147, v[112:115] offset:32768
	s_waitcnt vmcnt(1)
	ds_write_b128 v147, v[120:123] offset:40960
	v_add_u32_e32 v222, 0x12000, v153
	ds_write_b128 v222, v[116:119]
	s_waitcnt vmcnt(0)
	ds_write_b128 v222, v[124:127] offset:12288
	s_add_u32 s36, s36, 0xf0000
	s_addc_u32 s37, s37, 0
	s_add_i32 s35, s35, 1
	s_waitcnt lgkmcnt(0)
	s_barrier
	s_branch .Lfox_a_end
.Lfox_b_nop:
	s_add_u32 s36, s36, 0xf0000
	s_addc_u32 s37, s37, 0
	s_add_i32 s35, s35, 1
	v_add_u32_e32 v179, 0x400, v179
	s_branch .Lfox_b_end
.Lfox_b_so:
	v_lshl_add_u64 v[112:113], v[158:159], 0, s[36:37]
	v_add_co_u32_e32 v116, vcc, 0x70f1000, v112
	s_nop 1
	v_addc_co_u32_e32 v117, vcc, 0, v113, vcc
	v_add_co_u32_e32 v182, vcc, 0x7169000, v112
	s_nop 1
	v_addc_co_u32_e32 v183, vcc, 0, v113, vcc
	global_load_dwordx4 v[112:115], v[116:117], off offset:512
	s_nop 0
	global_load_dwordx4 v[116:119], v[116:117], off offset:1536
	global_load_dwordx4 v[120:123], v[182:183], off offset:512
	global_load_dwordx4 v[124:127], v[182:183], off offset:1536
	s_waitcnt vmcnt(3)
	ds_write_b128 v147, v[112:115] offset:16384
	s_waitcnt vmcnt(1)
	ds_write_b128 v147, v[120:123] offset:24576
	v_add_u32_e32 v222, 0xc000, v153
	ds_write_b128 v222, v[116:119]
	s_waitcnt vmcnt(0)
	ds_write_b128 v222, v[124:127] offset:12288
	s_add_u32 s36, s36, 0xf0000
	s_addc_u32 s37, s37, 0
	s_add_i32 s35, s35, 1
	v_add_u32_e32 v179, 0x400, v179
	s_waitcnt lgkmcnt(0)
	s_barrier
	s_branch .Lfox_b_end

.LBB0_593:
	s_load_dwordx2 s[10:11], s[0:1], 0
	s_waitcnt lgkmcnt(0)
	v_readlane_b32 s2, v253, 44
	s_load_dwordx2 s[10:11], s[0:1], 8
	s_waitcnt lgkmcnt(0)
	v_readlane_b32 s3, v253, 45
	s_load_dwordx2 s[10:11], s[0:1], 16
	s_waitcnt lgkmcnt(0)
	s_andn2_b64 vcc, exec, s[2:3]
	s_load_dwordx2 s[10:11], s[0:1], 24
	s_waitcnt lgkmcnt(0)
	s_mov_b32 s4, 0x10000
	s_load_dwordx2 s[10:11], s[0:1], 32
	s_waitcnt lgkmcnt(0)
	s_mov_b32 s9, 0x14000
	s_load_dwordx2 s[10:11], s[0:1], 40
	s_waitcnt lgkmcnt(0)
	s_mov_b32 s26, 0xc000
	s_load_dwordx2 s[10:11], s[0:1], 48
	s_waitcnt lgkmcnt(0)
	s_mov_b32 s27, 0x20000
	s_load_dwordx2 s[10:11], s[0:1], 56
	s_waitcnt lgkmcnt(0)
	s_mov_b32 s28, 0x24000
	s_load_dwordx2 s[10:11], s[0:1], 64
	s_waitcnt lgkmcnt(0)
	s_mov_b32 s29, 0x28000
	s_load_dwordx2 s[10:11], s[0:1], 0x48
	s_waitcnt lgkmcnt(0)
	s_mov_b32 s30, 0x2c000
	s_load_dwordx2 s[10:11], s[0:1], 0x50
	s_waitcnt lgkmcnt(0)
	s_mov_b32 s31, 0x30000
	s_load_dwordx2 s[10:11], s[0:1], 0x58
	s_waitcnt lgkmcnt(0)
	s_mov_b32 s34, 0x34000
	s_load_dwordx2 s[10:11], s[0:1], 0x60
	s_waitcnt lgkmcnt(0)
	s_load_dwordx2 s[18:19], s[0:1], 0x68
	s_waitcnt lgkmcnt(0)
	s_mov_b32 s35, 0x38000
	s_mov_b32 s36, 0x3c000
	s_add_u32 s10, s18, 0x1600000
	s_addc_u32 s11, s19, 0
	s_add_u32 s12, s18, 0x1800000
	s_addc_u32 s13, s19, 0
	s_add_u32 s14, s18, 0xe800000
	s_addc_u32 s15, s19, 0
	s_lshl_b32 s80, s16, 6
	s_lshl_b64 s[18:19], s[80:81], 2
	s_getpc_b64 s[20:21]
	s_add_u32 s20, s20, g_ctl@rel32@lo+14340
	s_addc_u32 s21, s21, g_ctl@rel32@hi+14348
	s_add_u32 s18, s20, s18
	v_readlane_b32 s2, v252, 9
	s_addc_u32 s19, s21, s19
	s_mov_b32 s20, s2
	v_readlane_b32 s3, v252, 10
	s_branch .LBB0_597

.LBB0_596:
	s_or_b64 exec, exec, s[22:23]
	s_barrier
	v_readfirstlane_b32 s3, v0
	s_nop 3
	s_cmp_gt_u32 s3, 0x7f
	s_cbranch_scc1 .LBB0_606
	s_lshr_b32 s24, s20, 4
	s_and_b32 s2, s20, 15
	v_lshrrev_b32_e32 v1, 5, v0
	v_lshl_add_u32 v1, s2, 2, v1
	v_and_b32_e32 v2, 31, v0
	v_lshlrev_b32_e32 v2, 1, v2
	v_lshl_add_u32 v3, v1, 6, v2
	v_lshlrev_b32_e32 v4, 2, v3
	v_lshlrev_b32_e32 v5, 2, v2
	v_lshlrev_b32_e32 v3, 1, v3
	s_lshl_b32 s3, s24, 19
	s_add_u32 s22, s12, s3
	s_addc_u32 s23, s13, 0
	s_lshl_b32 s3, s24, 13
	s_add_u32 s18, s10, s3
	s_addc_u32 s19, s11, 0
	s_lshl_b32 s3, s24, 18
	s_add_u32 s24, s14, s3
	s_addc_u32 s25, s15, 0
	v_mov_b32_e32 v6, 0
	v_mov_b32_e32 v7, 0
	global_load_dwordx2 v[10:11], v4, s[22:23] nt
	global_load_dwordx2 v[42:43], v5, s[18:19] offset:0
	s_add_u32 s22, s22, 0x4000
	s_addc_u32 s23, s23, 0
	global_load_dwordx2 v[12:13], v4, s[22:23] nt
	global_load_dwordx2 v[44:45], v5, s[18:19] offset:256
	s_add_u32 s22, s22, 0x4000
	s_addc_u32 s23, s23, 0
	global_load_dwordx2 v[14:15], v4, s[22:23] nt
	global_load_dwordx2 v[46:47], v5, s[18:19] offset:512
	s_add_u32 s22, s22, 0x4000
	s_addc_u32 s23, s23, 0
	global_load_dwordx2 v[16:17], v4, s[22:23] nt
	global_load_dwordx2 v[48:49], v5, s[18:19] offset:768
	s_add_u32 s22, s22, 0x4000
	s_addc_u32 s23, s23, 0
	global_load_dwordx2 v[18:19], v4, s[22:23] nt
	global_load_dwordx2 v[50:51], v5, s[18:19] offset:1024
	s_add_u32 s22, s22, 0x4000
	s_addc_u32 s23, s23, 0
	global_load_dwordx2 v[20:21], v4, s[22:23] nt
	global_load_dwordx2 v[52:53], v5, s[18:19] offset:1280
	s_add_u32 s22, s22, 0x4000
	s_addc_u32 s23, s23, 0
	global_load_dwordx2 v[22:23], v4, s[22:23] nt
	global_load_dwordx2 v[54:55], v5, s[18:19] offset:1536
	s_add_u32 s22, s22, 0x4000
	s_addc_u32 s23, s23, 0
	global_load_dwordx2 v[24:25], v4, s[22:23] nt
	global_load_dwordx2 v[56:57], v5, s[18:19] offset:1792
	s_add_u32 s22, s22, 0x4000
	s_addc_u32 s23, s23, 0
	global_load_dwordx2 v[26:27], v4, s[22:23] nt
	global_load_dwordx2 v[58:59], v5, s[18:19] offset:2048
	s_add_u32 s22, s22, 0x4000
	s_addc_u32 s23, s23, 0
	global_load_dwordx2 v[28:29], v4, s[22:23] nt
	global_load_dwordx2 v[60:61], v5, s[18:19] offset:2304
	s_add_u32 s22, s22, 0x4000
	s_addc_u32 s23, s23, 0
	global_load_dwordx2 v[30:31], v4, s[22:23] nt
	global_load_dwordx2 v[62:63], v5, s[18:19] offset:2560
	s_add_u32 s22, s22, 0x4000
	s_addc_u32 s23, s23, 0
	global_load_dwordx2 v[32:33], v4, s[22:23] nt
	global_load_dwordx2 v[64:65], v5, s[18:19] offset:2816
	s_add_u32 s22, s22, 0x4000
	s_addc_u32 s23, s23, 0
	global_load_dwordx2 v[34:35], v4, s[22:23] nt
	global_load_dwordx2 v[66:67], v5, s[18:19] offset:3072
	s_add_u32 s22, s22, 0x4000
	s_addc_u32 s23, s23, 0
	global_load_dwordx2 v[36:37], v4, s[22:23] nt
	global_load_dwordx2 v[68:69], v5, s[18:19] offset:3328
	s_add_u32 s22, s22, 0x4000
	s_addc_u32 s23, s23, 0
	global_load_dwordx2 v[38:39], v4, s[22:23] nt
	global_load_dwordx2 v[70:71], v5, s[18:19] offset:3584
	s_add_u32 s22, s22, 0x4000
	s_addc_u32 s23, s23, 0
	global_load_dwordx2 v[40:41], v4, s[22:23] nt
	global_load_dwordx2 v[72:73], v5, s[18:19] offset:3840
	s_add_u32 s22, s22, 0x4000
	s_addc_u32 s23, s23, 0
	s_add_u32 s18, s18, 0x1000
	s_addc_u32 s19, s19, 0
	v_cvt_pk_bf16_f32 v8, v6, v7
	global_store_dword v3, v8, s[24:25]
	s_add_u32 s24, s24, 0x2000
	s_addc_u32 s25, s25, 0
	s_waitcnt vmcnt(31)
	v_fma_f32 v6, v6, v42, v10
	v_fma_f32 v7, v7, v43, v11
	v_cvt_pk_bf16_f32 v8, v6, v7
	global_store_dword v3, v8, s[24:25]
	s_add_u32 s24, s24, 0x2000
	s_addc_u32 s25, s25, 0
	s_waitcnt vmcnt(30)
	v_fma_f32 v6, v6, v44, v12
	v_fma_f32 v7, v7, v45, v13
	v_cvt_pk_bf16_f32 v8, v6, v7
	global_store_dword v3, v8, s[24:25]
	s_add_u32 s24, s24, 0x2000
	s_addc_u32 s25, s25, 0
	s_waitcnt vmcnt(29)
	v_fma_f32 v6, v6, v46, v14
	v_fma_f32 v7, v7, v47, v15
	v_cvt_pk_bf16_f32 v8, v6, v7
	global_store_dword v3, v8, s[24:25]
	s_add_u32 s24, s24, 0x2000
	s_addc_u32 s25, s25, 0
	s_waitcnt vmcnt(28)
	v_fma_f32 v6, v6, v48, v16
	v_fma_f32 v7, v7, v49, v17
	v_cvt_pk_bf16_f32 v8, v6, v7
	global_store_dword v3, v8, s[24:25]
	s_add_u32 s24, s24, 0x2000
	s_addc_u32 s25, s25, 0
	s_waitcnt vmcnt(27)
	v_fma_f32 v6, v6, v50, v18
	v_fma_f32 v7, v7, v51, v19
	v_cvt_pk_bf16_f32 v8, v6, v7
	global_store_dword v3, v8, s[24:25]
	s_add_u32 s24, s24, 0x2000
	s_addc_u32 s25, s25, 0
	s_waitcnt vmcnt(26)
	v_fma_f32 v6, v6, v52, v20
	v_fma_f32 v7, v7, v53, v21
	v_cvt_pk_bf16_f32 v8, v6, v7
	global_store_dword v3, v8, s[24:25]
	s_add_u32 s24, s24, 0x2000
	s_addc_u32 s25, s25, 0
	s_waitcnt vmcnt(25)
	v_fma_f32 v6, v6, v54, v22
	v_fma_f32 v7, v7, v55, v23
	v_cvt_pk_bf16_f32 v8, v6, v7
	global_store_dword v3, v8, s[24:25]
	s_add_u32 s24, s24, 0x2000
	s_addc_u32 s25, s25, 0
	s_waitcnt vmcnt(24)
	v_fma_f32 v6, v6, v56, v24
	v_fma_f32 v7, v7, v57, v25
	v_cvt_pk_bf16_f32 v8, v6, v7
	global_store_dword v3, v8, s[24:25]
	s_add_u32 s24, s24, 0x2000
	s_addc_u32 s25, s25, 0
	s_waitcnt vmcnt(23)
	v_fma_f32 v6, v6, v58, v26
	v_fma_f32 v7, v7, v59, v27
	v_cvt_pk_bf16_f32 v8, v6, v7
	global_store_dword v3, v8, s[24:25]
	s_add_u32 s24, s24, 0x2000
	s_addc_u32 s25, s25, 0
	s_waitcnt vmcnt(22)
	v_fma_f32 v6, v6, v60, v28
	v_fma_f32 v7, v7, v61, v29
	v_cvt_pk_bf16_f32 v8, v6, v7
	global_store_dword v3, v8, s[24:25]
	s_add_u32 s24, s24, 0x2000
	s_addc_u32 s25, s25, 0
	s_waitcnt vmcnt(21)
	v_fma_f32 v6, v6, v62, v30
	v_fma_f32 v7, v7, v63, v31
	v_cvt_pk_bf16_f32 v8, v6, v7
	global_store_dword v3, v8, s[24:25]
	s_add_u32 s24, s24, 0x2000
	s_addc_u32 s25, s25, 0
	s_waitcnt vmcnt(20)
	v_fma_f32 v6, v6, v64, v32
	v_fma_f32 v7, v7, v65, v33
	v_cvt_pk_bf16_f32 v8, v6, v7
	global_store_dword v3, v8, s[24:25]
	s_add_u32 s24, s24, 0x2000
	s_addc_u32 s25, s25, 0
	s_waitcnt vmcnt(19)
	v_fma_f32 v6, v6, v66, v34
	v_fma_f32 v7, v7, v67, v35
	v_cvt_pk_bf16_f32 v8, v6, v7
	global_store_dword v3, v8, s[24:25]
	s_add_u32 s24, s24, 0x2000
	s_addc_u32 s25, s25, 0
	s_waitcnt vmcnt(18)
	v_fma_f32 v6, v6, v68, v36
	v_fma_f32 v7, v7, v69, v37
	v_cvt_pk_bf16_f32 v8, v6, v7
	global_store_dword v3, v8, s[24:25]
	s_add_u32 s24, s24, 0x2000
	s_addc_u32 s25, s25, 0
	s_waitcnt vmcnt(17)
	v_fma_f32 v6, v6, v70, v38
	v_fma_f32 v7, v7, v71, v39
	v_cvt_pk_bf16_f32 v8, v6, v7
	global_store_dword v3, v8, s[24:25]
	s_add_u32 s24, s24, 0x2000
	s_addc_u32 s25, s25, 0
	s_waitcnt vmcnt(16)
	v_fma_f32 v6, v6, v72, v40
	v_fma_f32 v7, v7, v73, v41
	global_load_dwordx2 v[10:11], v4, s[22:23] nt
	global_load_dwordx2 v[42:43], v5, s[18:19] offset:0
	s_add_u32 s22, s22, 0x4000
	s_addc_u32 s23, s23, 0
	global_load_dwordx2 v[12:13], v4, s[22:23] nt
	global_load_dwordx2 v[44:45], v5, s[18:19] offset:256
	s_add_u32 s22, s22, 0x4000
	s_addc_u32 s23, s23, 0
	global_load_dwordx2 v[14:15], v4, s[22:23] nt
	global_load_dwordx2 v[46:47], v5, s[18:19] offset:512
	s_add_u32 s22, s22, 0x4000
	s_addc_u32 s23, s23, 0
	global_load_dwordx2 v[16:17], v4, s[22:23] nt
	global_load_dwordx2 v[48:49], v5, s[18:19] offset:768
	s_add_u32 s22, s22, 0x4000
	s_addc_u32 s23, s23, 0
	global_load_dwordx2 v[18:19], v4, s[22:23] nt
	global_load_dwordx2 v[50:51], v5, s[18:19] offset:1024
	s_add_u32 s22, s22, 0x4000
	s_addc_u32 s23, s23, 0
	global_load_dwordx2 v[20:21], v4, s[22:23] nt
	global_load_dwordx2 v[52:53], v5, s[18:19] offset:1280
	s_add_u32 s22, s22, 0x4000
	s_addc_u32 s23, s23, 0
	global_load_dwordx2 v[22:23], v4, s[22:23] nt
	global_load_dwordx2 v[54:55], v5, s[18:19] offset:1536
	s_add_u32 s22, s22, 0x4000
	s_addc_u32 s23, s23, 0
	global_load_dwordx2 v[24:25], v4, s[22:23] nt
	global_load_dwordx2 v[56:57], v5, s[18:19] offset:1792
	s_add_u32 s22, s22, 0x4000
	s_addc_u32 s23, s23, 0
	global_load_dwordx2 v[26:27], v4, s[22:23] nt
	global_load_dwordx2 v[58:59], v5, s[18:19] offset:2048
	s_add_u32 s22, s22, 0x4000
	s_addc_u32 s23, s23, 0
	global_load_dwordx2 v[28:29], v4, s[22:23] nt
	global_load_dwordx2 v[60:61], v5, s[18:19] offset:2304
	s_add_u32 s22, s22, 0x4000
	s_addc_u32 s23, s23, 0
	global_load_dwordx2 v[30:31], v4, s[22:23] nt
	global_load_dwordx2 v[62:63], v5, s[18:19] offset:2560
	s_add_u32 s22, s22, 0x4000
	s_addc_u32 s23, s23, 0
	global_load_dwordx2 v[32:33], v4, s[22:23] nt
	global_load_dwordx2 v[64:65], v5, s[18:19] offset:2816
	s_add_u32 s22, s22, 0x4000
	s_addc_u32 s23, s23, 0
	global_load_dwordx2 v[34:35], v4, s[22:23] nt
	global_load_dwordx2 v[66:67], v5, s[18:19] offset:3072
	s_add_u32 s22, s22, 0x4000
	s_addc_u32 s23, s23, 0
	global_load_dwordx2 v[36:37], v4, s[22:23] nt
	global_load_dwordx2 v[68:69], v5, s[18:19] offset:3328
	s_add_u32 s22, s22, 0x4000
	s_addc_u32 s23, s23, 0
	global_load_dwordx2 v[38:39], v4, s[22:23] nt
	global_load_dwordx2 v[70:71], v5, s[18:19] offset:3584
	s_add_u32 s22, s22, 0x4000
	s_addc_u32 s23, s23, 0
	global_load_dwordx2 v[40:41], v4, s[22:23] nt
	global_load_dwordx2 v[72:73], v5, s[18:19] offset:3840
	s_add_u32 s22, s22, 0x4000
	s_addc_u32 s23, s23, 0
	s_add_u32 s18, s18, 0x1000
	s_addc_u32 s19, s19, 0
	v_cvt_pk_bf16_f32 v8, v6, v7
	global_store_dword v3, v8, s[24:25]
	s_add_u32 s24, s24, 0x2000
	s_addc_u32 s25, s25, 0
	s_waitcnt vmcnt(31)
	v_fma_f32 v6, v6, v42, v10
	v_fma_f32 v7, v7, v43, v11
	v_cvt_pk_bf16_f32 v8, v6, v7
	global_store_dword v3, v8, s[24:25]
	s_add_u32 s24, s24, 0x2000
	s_addc_u32 s25, s25, 0
	s_waitcnt vmcnt(30)
	v_fma_f32 v6, v6, v44, v12
	v_fma_f32 v7, v7, v45, v13
	v_cvt_pk_bf16_f32 v8, v6, v7
	global_store_dword v3, v8, s[24:25]
	s_add_u32 s24, s24, 0x2000
	s_addc_u32 s25, s25, 0
	s_waitcnt vmcnt(29)
	v_fma_f32 v6, v6, v46, v14
	v_fma_f32 v7, v7, v47, v15
	v_cvt_pk_bf16_f32 v8, v6, v7
	global_store_dword v3, v8, s[24:25]
	s_add_u32 s24, s24, 0x2000
	s_addc_u32 s25, s25, 0
	s_waitcnt vmcnt(28)
	v_fma_f32 v6, v6, v48, v16
	v_fma_f32 v7, v7, v49, v17
	v_cvt_pk_bf16_f32 v8, v6, v7
	global_store_dword v3, v8, s[24:25]
	s_add_u32 s24, s24, 0x2000
	s_addc_u32 s25, s25, 0
	s_waitcnt vmcnt(27)
	v_fma_f32 v6, v6, v50, v18
	v_fma_f32 v7, v7, v51, v19
	v_cvt_pk_bf16_f32 v8, v6, v7
	global_store_dword v3, v8, s[24:25]
	s_add_u32 s24, s24, 0x2000
	s_addc_u32 s25, s25, 0
	s_waitcnt vmcnt(26)
	v_fma_f32 v6, v6, v52, v20
	v_fma_f32 v7, v7, v53, v21
	v_cvt_pk_bf16_f32 v8, v6, v7
	global_store_dword v3, v8, s[24:25]
	s_add_u32 s24, s24, 0x2000
	s_addc_u32 s25, s25, 0
	s_waitcnt vmcnt(25)
	v_fma_f32 v6, v6, v54, v22
	v_fma_f32 v7, v7, v55, v23
	v_cvt_pk_bf16_f32 v8, v6, v7
	global_store_dword v3, v8, s[24:25]
	s_add_u32 s24, s24, 0x2000
	s_addc_u32 s25, s25, 0
	s_waitcnt vmcnt(24)
	v_fma_f32 v6, v6, v56, v24
	v_fma_f32 v7, v7, v57, v25
	v_cvt_pk_bf16_f32 v8, v6, v7
	global_store_dword v3, v8, s[24:25]
	s_add_u32 s24, s24, 0x2000
	s_addc_u32 s25, s25, 0
	s_waitcnt vmcnt(23)
	v_fma_f32 v6, v6, v58, v26
	v_fma_f32 v7, v7, v59, v27
	v_cvt_pk_bf16_f32 v8, v6, v7
	global_store_dword v3, v8, s[24:25]
	s_add_u32 s24, s24, 0x2000
	s_addc_u32 s25, s25, 0
	s_waitcnt vmcnt(22)
	v_fma_f32 v6, v6, v60, v28
	v_fma_f32 v7, v7, v61, v29
	v_cvt_pk_bf16_f32 v8, v6, v7
	global_store_dword v3, v8, s[24:25]
	s_add_u32 s24, s24, 0x2000
	s_addc_u32 s25, s25, 0
	s_waitcnt vmcnt(21)
	v_fma_f32 v6, v6, v62, v30
	v_fma_f32 v7, v7, v63, v31
	v_cvt_pk_bf16_f32 v8, v6, v7
	global_store_dword v3, v8, s[24:25]
	s_add_u32 s24, s24, 0x2000
	s_addc_u32 s25, s25, 0
	s_waitcnt vmcnt(20)
	v_fma_f32 v6, v6, v64, v32
	v_fma_f32 v7, v7, v65, v33
	v_cvt_pk_bf16_f32 v8, v6, v7
	global_store_dword v3, v8, s[24:25]
	s_add_u32 s24, s24, 0x2000
	s_addc_u32 s25, s25, 0
	s_waitcnt vmcnt(19)
	v_fma_f32 v6, v6, v66, v34
	v_fma_f32 v7, v7, v67, v35
	v_cvt_pk_bf16_f32 v8, v6, v7
	global_store_dword v3, v8, s[24:25]
	s_add_u32 s24, s24, 0x2000
	s_addc_u32 s25, s25, 0
	s_waitcnt vmcnt(18)
	v_fma_f32 v6, v6, v68, v36
	v_fma_f32 v7, v7, v69, v37
	v_cvt_pk_bf16_f32 v8, v6, v7
	global_store_dword v3, v8, s[24:25]
	s_add_u32 s24, s24, 0x2000
	s_addc_u32 s25, s25, 0
	s_waitcnt vmcnt(17)
	v_fma_f32 v6, v6, v70, v38
	v_fma_f32 v7, v7, v71, v39
	v_cvt_pk_bf16_f32 v8, v6, v7
	global_store_dword v3, v8, s[24:25]
	s_add_u32 s24, s24, 0x2000
	s_addc_u32 s25, s25, 0
	s_waitcnt vmcnt(16)
	v_fma_f32 v6, v6, v72, v40
	v_fma_f32 v7, v7, v73, v41
	s_branch .LBB0_606

	.amdhsa_kernel _Z10fwd_kernel4Args
		.amdhsa_group_segment_fixed_size 0
		.amdhsa_private_segment_fixed_size 0
		.amdhsa_kernarg_size 368
		.amdhsa_user_sgpr_count 2
		.amdhsa_user_sgpr_dispatch_ptr 0
		.amdhsa_user_sgpr_queue_ptr 0
		.amdhsa_user_sgpr_kernarg_segment_ptr 1
		.amdhsa_user_sgpr_dispatch_id 0
		.amdhsa_user_sgpr_kernarg_preload_length 0
		.amdhsa_user_sgpr_kernarg_preload_offset 0
		.amdhsa_user_sgpr_private_segment_size 0
		.amdhsa_uses_dynamic_stack 0
		.amdhsa_enable_private_segment 0
		.amdhsa_system_sgpr_workgroup_id_x 1
		.amdhsa_system_sgpr_workgroup_id_y 0
		.amdhsa_system_sgpr_workgroup_id_z 0
		.amdhsa_system_sgpr_workgroup_info 0
		.amdhsa_system_vgpr_workitem_id 2
		.amdhsa_next_free_vgpr 256
		.amdhsa_next_free_sgpr 102
		.amdhsa_accum_offset 256
		.amdhsa_reserve_vcc 1
		.amdhsa_float_round_mode_32 0
		.amdhsa_float_round_mode_16_64 0
		.amdhsa_float_denorm_mode_32 3
		.amdhsa_float_denorm_mode_16_64 3
		.amdhsa_dx10_clamp 1
		.amdhsa_ieee_mode 1
		.amdhsa_fp16_overflow 0
		.amdhsa_tg_split 0
		.amdhsa_exception_fp_ieee_invalid_op 0
		.amdhsa_exception_fp_denorm_src 0
		.amdhsa_exception_fp_ieee_div_zero 0
		.amdhsa_exception_fp_ieee_overflow 0
		.amdhsa_exception_fp_ieee_underflow 0
		.amdhsa_exception_fp_ieee_inexact 0
		.amdhsa_exception_int_div_zero 0
	.end_amdhsa_kernel

amdhsa.kernels:
  - .agpr_count:     0
    .args:
      - .offset:         0
        .size:           112
        .value_kind:     by_value
      - .offset:         112
        .size:           4
        .value_kind:     hidden_block_count_x
      - .offset:         116
        .size:           4
        .value_kind:     hidden_block_count_y
      - .offset:         120
        .size:           4
        .value_kind:     hidden_block_count_z
      - .offset:         124
        .size:           2
        .value_kind:     hidden_group_size_x
      - .offset:         126
        .size:           2
        .value_kind:     hidden_group_size_y
      - .offset:         128
        .size:           2
        .value_kind:     hidden_group_size_z
      - .offset:         130
        .size:           2
        .value_kind:     hidden_remainder_x
      - .offset:         132
        .size:           2
        .value_kind:     hidden_remainder_y
      - .offset:         134
        .size:           2
        .value_kind:     hidden_remainder_z
      - .offset:         152
        .size:           8
        .value_kind:     hidden_global_offset_x
      - .offset:         160
        .size:           8
        .value_kind:     hidden_global_offset_y
      - .offset:         168
        .size:           8
        .value_kind:     hidden_global_offset_z
      - .offset:         176
        .size:           2
        .value_kind:     hidden_grid_dims
      - .offset:         200
        .size:           8
        .value_kind:     hidden_multigrid_sync_arg
      - .offset:         232
        .size:           4
        .value_kind:     hidden_dynamic_lds_size
    .group_segment_fixed_size: 0
    .kernarg_segment_align: 8
    .kernarg_segment_size: 368
    .language:       OpenCL C
    .language_version:
      - 2
      - 0
    .max_flat_workgroup_size: 512
    .name:           _Z10fwd_kernel4Args
    .private_segment_fixed_size: 0
    .sgpr_count:     108
    .sgpr_spill_count: 96
    .symbol:         _Z10fwd_kernel4Args.kd
    .uniform_work_group_size: 1
    .uses_dynamic_stack: false
    .vgpr_count:     256
    .vgpr_spill_count: 0
    .wavefront_size: 64
